# s_setprio 1 over the MFMA run of every 64-deep GEMM K block (0 again before the block-top waits)
# speedup vs baseline: 1.0373x; 1.0075x over previous
.Lg_ph5_noB:
	s_setprio 1
	s_waitcnt lgkmcnt(3)
	v_mfma_f32_16x16x32_bf16 v[0:3], v[170:173], v[190:193], v[0:3]
	v_mfma_f32_16x16x32_bf16 v[4:7], v[170:173], v[194:197], v[4:7]
	v_mfma_f32_16x16x32_bf16 v[8:11], v[170:173], v[198:201], v[8:11]
	v_mfma_f32_16x16x32_bf16 v[12:15], v[170:173], v[202:205], v[12:15]
	ds_read_b128 v[170:173], v138 offset:8192
	s_waitcnt lgkmcnt(3)
	v_mfma_f32_16x16x32_bf16 v[16:19], v[174:177], v[190:193], v[16:19]
	v_mfma_f32_16x16x32_bf16 v[20:23], v[174:177], v[194:197], v[20:23]
	v_mfma_f32_16x16x32_bf16 v[24:27], v[174:177], v[198:201], v[24:27]
	v_mfma_f32_16x16x32_bf16 v[28:31], v[174:177], v[202:205], v[28:31]
	ds_read_b128 v[174:177], v138 offset:10240
	s_waitcnt lgkmcnt(3)
	v_mfma_f32_16x16x32_bf16 v[32:35], v[182:185], v[190:193], v[32:35]
	v_mfma_f32_16x16x32_bf16 v[36:39], v[182:185], v[194:197], v[36:39]
	v_mfma_f32_16x16x32_bf16 v[40:43], v[182:185], v[198:201], v[40:43]
	v_mfma_f32_16x16x32_bf16 v[44:47], v[182:185], v[202:205], v[44:47]
	ds_read_b128 v[182:185], v138 offset:12288
	s_waitcnt lgkmcnt(3)
	v_mfma_f32_16x16x32_bf16 v[48:51], v[186:189], v[190:193], v[48:51]
	v_mfma_f32_16x16x32_bf16 v[52:55], v[186:189], v[194:197], v[52:55]
	v_mfma_f32_16x16x32_bf16 v[56:59], v[186:189], v[198:201], v[56:59]
	v_mfma_f32_16x16x32_bf16 v[60:63], v[186:189], v[202:205], v[60:63]
	ds_read_b128 v[186:189], v138 offset:14336
	s_waitcnt lgkmcnt(3)
	v_mfma_f32_16x16x32_bf16 v[64:67], v[170:173], v[190:193], v[64:67]
	v_mfma_f32_16x16x32_bf16 v[68:71], v[170:173], v[194:197], v[68:71]
	v_mfma_f32_16x16x32_bf16 v[72:75], v[170:173], v[198:201], v[72:75]
	v_mfma_f32_16x16x32_bf16 v[76:79], v[170:173], v[202:205], v[76:79]
	ds_read_b128 v[170:173], v139
	s_waitcnt lgkmcnt(3)
	v_mfma_f32_16x16x32_bf16 v[80:83], v[174:177], v[190:193], v[80:83]
	v_mfma_f32_16x16x32_bf16 v[84:87], v[174:177], v[194:197], v[84:87]
	v_mfma_f32_16x16x32_bf16 v[88:91], v[174:177], v[198:201], v[88:91]
	v_mfma_f32_16x16x32_bf16 v[92:95], v[174:177], v[202:205], v[92:95]
	ds_read_b128 v[174:177], v139 offset:2048
	s_waitcnt lgkmcnt(3)
	v_mfma_f32_16x16x32_bf16 v[96:99], v[182:185], v[190:193], v[96:99]
	v_mfma_f32_16x16x32_bf16 v[100:103], v[182:185], v[194:197], v[100:103]
	v_mfma_f32_16x16x32_bf16 v[104:107], v[182:185], v[198:201], v[104:107]
	v_mfma_f32_16x16x32_bf16 v[108:111], v[182:185], v[202:205], v[108:111]
	ds_read_b128 v[182:185], v139 offset:4096
	s_waitcnt lgkmcnt(3)
	v_mfma_f32_16x16x32_bf16 v[112:115], v[186:189], v[190:193], v[112:115]
	v_mfma_f32_16x16x32_bf16 v[116:119], v[186:189], v[194:197], v[116:119]
	v_mfma_f32_16x16x32_bf16 v[120:123], v[186:189], v[198:201], v[120:123]
	v_mfma_f32_16x16x32_bf16 v[124:127], v[186:189], v[202:205], v[124:127]
	ds_read_b128 v[186:189], v139 offset:6144
	s_waitcnt lgkmcnt(3)
	v_mfma_f32_16x16x32_bf16 v[0:3], v[170:173], v[206:209], v[0:3]
	v_mfma_f32_16x16x32_bf16 v[4:7], v[170:173], v[222:225], v[4:7]
	v_mfma_f32_16x16x32_bf16 v[8:11], v[170:173], v[226:229], v[8:11]
	v_mfma_f32_16x16x32_bf16 v[12:15], v[170:173], v[230:233], v[12:15]
	ds_read_b128 v[170:173], v139 offset:8192
	s_waitcnt lgkmcnt(3)
	v_mfma_f32_16x16x32_bf16 v[16:19], v[174:177], v[206:209], v[16:19]
	v_mfma_f32_16x16x32_bf16 v[20:23], v[174:177], v[222:225], v[20:23]
	v_mfma_f32_16x16x32_bf16 v[24:27], v[174:177], v[226:229], v[24:27]
	v_mfma_f32_16x16x32_bf16 v[28:31], v[174:177], v[230:233], v[28:31]
	ds_read_b128 v[174:177], v139 offset:10240
	s_waitcnt lgkmcnt(3)
	v_mfma_f32_16x16x32_bf16 v[32:35], v[182:185], v[206:209], v[32:35]
	v_mfma_f32_16x16x32_bf16 v[36:39], v[182:185], v[222:225], v[36:39]
	v_mfma_f32_16x16x32_bf16 v[40:43], v[182:185], v[226:229], v[40:43]
	v_mfma_f32_16x16x32_bf16 v[44:47], v[182:185], v[230:233], v[44:47]
	ds_read_b128 v[182:185], v139 offset:12288
	s_waitcnt lgkmcnt(3)
	v_mfma_f32_16x16x32_bf16 v[48:51], v[186:189], v[206:209], v[48:51]
	v_mfma_f32_16x16x32_bf16 v[52:55], v[186:189], v[222:225], v[52:55]
	v_mfma_f32_16x16x32_bf16 v[56:59], v[186:189], v[226:229], v[56:59]
	v_mfma_f32_16x16x32_bf16 v[60:63], v[186:189], v[230:233], v[60:63]
	ds_read_b128 v[186:189], v139 offset:14336
	s_waitcnt lgkmcnt(3)
	v_mfma_f32_16x16x32_bf16 v[64:67], v[170:173], v[206:209], v[64:67]
	v_mfma_f32_16x16x32_bf16 v[68:71], v[170:173], v[222:225], v[68:71]
	v_mfma_f32_16x16x32_bf16 v[72:75], v[170:173], v[226:229], v[72:75]
	v_mfma_f32_16x16x32_bf16 v[76:79], v[170:173], v[230:233], v[76:79]
	s_waitcnt lgkmcnt(2)
	v_mfma_f32_16x16x32_bf16 v[80:83], v[174:177], v[206:209], v[80:83]
	v_mfma_f32_16x16x32_bf16 v[84:87], v[174:177], v[222:225], v[84:87]
	v_mfma_f32_16x16x32_bf16 v[88:91], v[174:177], v[226:229], v[88:91]
	v_mfma_f32_16x16x32_bf16 v[92:95], v[174:177], v[230:233], v[92:95]
	s_waitcnt lgkmcnt(1)
	v_mfma_f32_16x16x32_bf16 v[96:99], v[182:185], v[206:209], v[96:99]
	v_mfma_f32_16x16x32_bf16 v[100:103], v[182:185], v[222:225], v[100:103]
	v_mfma_f32_16x16x32_bf16 v[104:107], v[182:185], v[226:229], v[104:107]
	v_mfma_f32_16x16x32_bf16 v[108:111], v[182:185], v[230:233], v[108:111]
	s_waitcnt lgkmcnt(0)
	v_mfma_f32_16x16x32_bf16 v[112:115], v[186:189], v[206:209], v[112:115]
	v_mfma_f32_16x16x32_bf16 v[116:119], v[186:189], v[222:225], v[116:119]
	v_mfma_f32_16x16x32_bf16 v[120:123], v[186:189], v[226:229], v[120:123]
	v_mfma_f32_16x16x32_bf16 v[124:127], v[186:189], v[230:233], v[124:127]
	s_setprio 0
	v_xor_b32_e32 v138, 0x8000, v138
	v_xor_b32_e32 v139, 0x8000, v139
	s_xor_b32 s15, s15, 0x8000
	s_add_i32 s14, s14, 1
	s_cmp_eq_u32 s14, 16
	s_cbranch_scc0 .Lg_ph5_top
	s_waitcnt vmcnt(0)
	v_mov_b32_e32 v130, v180
	v_add_u32_e32 v201, 0x400, v153
	v_add_u32_e32 v200, 0x1000, v153
	v_add_u32_e32 v199, 0x1400, v153
	v_add_u32_e32 v198, 0x2000, v153
	v_add_u32_e32 v192, 0x2400, v153
	v_add_u32_e32 v193, 0x3000, v153
	v_add_u32_e32 v194, 0x3200, v153
	v_add_u32_e32 v195, 0x3400, v153
	v_add_u32_e32 v196, 0x3600, v153
	v_add_u32_e32 v197, 0x4000, v153
	v_add_u32_e32 v189, 0x4400, v153
	v_add_u32_e32 v190, 0x4800, v153
	v_add_u32_e32 v191, 0x5000, v153
	v_add_u32_e32 v186, 0x5400, v153
	v_add_u32_e32 v187, 0x5800, v153
	v_add_u32_e32 v188, 0x6000, v153
	v_add_u32_e32 v179, 0x6400, v153
	v_add_u32_e32 v181, 0x6800, v153
	v_add_u32_e32 v182, 0x7200, v153
	v_add_u32_e32 v183, 0x7400, v153
	v_add_u32_e32 v184, 0x7600, v153
	v_add_u32_e32 v185, 0x7800, v153
	v_add_u32_e32 v178, 0x8400, v153
	v_add_u32_e32 v177, 0x8800, v153
	v_add_u32_e32 v176, 0x9400, v153
	v_add_u32_e32 v175, 0x9800, v153
	v_add_u32_e32 v174, 0xa400, v153
	v_add_u32_e32 v147, 0xa800, v153
	v_add_u32_e32 v169, 0xb400, v153
	v_add_u32_e32 v170, 0xb600, v153
	v_add_u32_e32 v171, 0xb800, v153
	v_add_u32_e32 v172, 0xba00, v153
	s_waitcnt vmcnt(0)
	s_barrier
	s_and_saveexec_b64 s[14:15], s[6:7]
	s_cbranch_execz .LBB0_605
	v_and_b32_e32 v254, 63, v180
	v_lshrrev_b32_e32 v253, 4, v254
	v_mul_u32_u24_e32 v253, 0x840, v253
	v_and_b32_e32 v254, 15, v254
	v_lshl_add_u32 v253, v254, 2, v253
	v_and_b32_e32 v254, 64, v180
	v_lshl_add_u32 v253, v254, 2, v253
	ds_write_b32 v253, v0 offset:0
	ds_write_b32 v253, v1 offset:528
	ds_write_b32 v253, v2 offset:1056
	ds_write_b32 v253, v3 offset:1584
	ds_write_b32 v253, v4 offset:64
	ds_write_b32 v253, v5 offset:592
	ds_write_b32 v253, v6 offset:1120
	ds_write_b32 v253, v7 offset:1648
	ds_write_b32 v253, v8 offset:128
	ds_write_b32 v253, v9 offset:656
	ds_write_b32 v253, v10 offset:1184
	ds_write_b32 v253, v11 offset:1712
	ds_write_b32 v253, v12 offset:192
	ds_write_b32 v253, v13 offset:720
	ds_write_b32 v253, v14 offset:1248
	ds_write_b32 v253, v15 offset:1776
	ds_write_b32 v253, v16 offset:8448
	ds_write_b32 v253, v17 offset:8976
	ds_write_b32 v253, v18 offset:9504
	ds_write_b32 v253, v19 offset:10032
	ds_write_b32 v253, v20 offset:8512
	ds_write_b32 v253, v21 offset:9040
	ds_write_b32 v253, v22 offset:9568
	ds_write_b32 v253, v23 offset:10096
	ds_write_b32 v253, v24 offset:8576
	ds_write_b32 v253, v25 offset:9104
	ds_write_b32 v253, v26 offset:9632
	ds_write_b32 v253, v27 offset:10160
	ds_write_b32 v253, v28 offset:8640
	ds_write_b32 v253, v29 offset:9168
	ds_write_b32 v253, v30 offset:9696
	ds_write_b32 v253, v31 offset:10224
	ds_write_b32 v253, v32 offset:16896
	ds_write_b32 v253, v33 offset:17424
	ds_write_b32 v253, v34 offset:17952
	ds_write_b32 v253, v35 offset:18480
	ds_write_b32 v253, v36 offset:16960
	ds_write_b32 v253, v37 offset:17488
	ds_write_b32 v253, v38 offset:18016
	ds_write_b32 v253, v39 offset:18544
	ds_write_b32 v253, v40 offset:17024
	ds_write_b32 v253, v41 offset:17552
	ds_write_b32 v253, v42 offset:18080
	ds_write_b32 v253, v43 offset:18608
	ds_write_b32 v253, v44 offset:17088
	ds_write_b32 v253, v45 offset:17616
	ds_write_b32 v253, v46 offset:18144
	ds_write_b32 v253, v47 offset:18672
	ds_write_b32 v253, v48 offset:25344
	ds_write_b32 v253, v49 offset:25872
	ds_write_b32 v253, v50 offset:26400
	ds_write_b32 v253, v51 offset:26928
	ds_write_b32 v253, v52 offset:25408
	ds_write_b32 v253, v53 offset:25936
	ds_write_b32 v253, v54 offset:26464
	ds_write_b32 v253, v55 offset:26992
	ds_write_b32 v253, v56 offset:25472
	ds_write_b32 v253, v57 offset:26000
	ds_write_b32 v253, v58 offset:26528
	ds_write_b32 v253, v59 offset:27056
	ds_write_b32 v253, v60 offset:25536
	ds_write_b32 v253, v61 offset:26064
	ds_write_b32 v253, v62 offset:26592
	ds_write_b32 v253, v63 offset:27120
	ds_write_b32 v253, v64 offset:33792
	ds_write_b32 v253, v65 offset:34320
	ds_write_b32 v253, v66 offset:34848
	ds_write_b32 v253, v67 offset:35376
	ds_write_b32 v253, v68 offset:33856
	ds_write_b32 v253, v69 offset:34384
	ds_write_b32 v253, v70 offset:34912
	ds_write_b32 v253, v71 offset:35440
	ds_write_b32 v253, v72 offset:33920
	ds_write_b32 v253, v73 offset:34448
	ds_write_b32 v253, v74 offset:34976
	ds_write_b32 v253, v75 offset:35504
	ds_write_b32 v253, v76 offset:33984
	ds_write_b32 v253, v77 offset:34512
	ds_write_b32 v253, v78 offset:35040
	ds_write_b32 v253, v79 offset:35568
	ds_write_b32 v253, v80 offset:42240
	ds_write_b32 v253, v81 offset:42768
	ds_write_b32 v253, v82 offset:43296
	ds_write_b32 v253, v83 offset:43824
	ds_write_b32 v253, v84 offset:42304
	ds_write_b32 v253, v85 offset:42832
	ds_write_b32 v253, v86 offset:43360
	ds_write_b32 v253, v87 offset:43888
	ds_write_b32 v253, v88 offset:42368
	ds_write_b32 v253, v89 offset:42896
	ds_write_b32 v253, v90 offset:43424
	ds_write_b32 v253, v91 offset:43952
	ds_write_b32 v253, v92 offset:42432
	ds_write_b32 v253, v93 offset:42960
	ds_write_b32 v253, v94 offset:43488
	ds_write_b32 v253, v95 offset:44016
	ds_write_b32 v253, v96 offset:50688
	ds_write_b32 v253, v97 offset:51216
	ds_write_b32 v253, v98 offset:51744
	ds_write_b32 v253, v99 offset:52272
	ds_write_b32 v253, v100 offset:50752
	ds_write_b32 v253, v101 offset:51280
	ds_write_b32 v253, v102 offset:51808
	ds_write_b32 v253, v103 offset:52336
	ds_write_b32 v253, v104 offset:50816
	ds_write_b32 v253, v105 offset:51344
	ds_write_b32 v253, v106 offset:51872
	ds_write_b32 v253, v107 offset:52400
	ds_write_b32 v253, v108 offset:50880
	ds_write_b32 v253, v109 offset:51408
	ds_write_b32 v253, v110 offset:51936
	ds_write_b32 v253, v111 offset:52464
	ds_write_b32 v253, v112 offset:59136
	ds_write_b32 v253, v113 offset:59664
	ds_write_b32 v253, v114 offset:60192
	ds_write_b32 v253, v115 offset:60720
	ds_write_b32 v253, v116 offset:59200
	ds_write_b32 v253, v117 offset:59728
	ds_write_b32 v253, v118 offset:60256
	ds_write_b32 v253, v119 offset:60784
	ds_write_b32 v253, v120 offset:59264
	ds_write_b32 v253, v121 offset:59792
	ds_write_b32 v253, v122 offset:60320
	ds_write_b32 v253, v123 offset:60848
	ds_write_b32 v253, v124 offset:59328
	ds_write_b32 v253, v125 offset:59856
	ds_write_b32 v253, v126 offset:60384
	ds_write_b32 v253, v127 offset:60912

.Lg_ph8_noB:
	s_setprio 1
	s_waitcnt lgkmcnt(3)
	v_mfma_f32_16x16x32_bf16 v[0:3], v[166:169], v[190:193], v[0:3]
	v_mfma_f32_16x16x32_bf16 v[4:7], v[166:169], v[194:197], v[4:7]
	v_mfma_f32_16x16x32_bf16 v[8:11], v[166:169], v[198:201], v[8:11]
	v_mfma_f32_16x16x32_bf16 v[12:15], v[166:169], v[202:205], v[12:15]
	ds_read_b128 v[166:169], v138 offset:8192
	s_waitcnt lgkmcnt(3)
	v_mfma_f32_16x16x32_bf16 v[16:19], v[170:173], v[190:193], v[16:19]
	v_mfma_f32_16x16x32_bf16 v[20:23], v[170:173], v[194:197], v[20:23]
	v_mfma_f32_16x16x32_bf16 v[24:27], v[170:173], v[198:201], v[24:27]
	v_mfma_f32_16x16x32_bf16 v[28:31], v[170:173], v[202:205], v[28:31]
	ds_read_b128 v[170:173], v138 offset:10240
	s_waitcnt lgkmcnt(3)
	v_mfma_f32_16x16x32_bf16 v[32:35], v[174:177], v[190:193], v[32:35]
	v_mfma_f32_16x16x32_bf16 v[36:39], v[174:177], v[194:197], v[36:39]
	v_mfma_f32_16x16x32_bf16 v[40:43], v[174:177], v[198:201], v[40:43]
	v_mfma_f32_16x16x32_bf16 v[44:47], v[174:177], v[202:205], v[44:47]
	ds_read_b128 v[174:177], v138 offset:12288
	s_waitcnt lgkmcnt(3)
	v_mfma_f32_16x16x32_bf16 v[48:51], v[182:185], v[190:193], v[48:51]
	v_mfma_f32_16x16x32_bf16 v[52:55], v[182:185], v[194:197], v[52:55]
	v_mfma_f32_16x16x32_bf16 v[56:59], v[182:185], v[198:201], v[56:59]
	v_mfma_f32_16x16x32_bf16 v[60:63], v[182:185], v[202:205], v[60:63]
	ds_read_b128 v[182:185], v138 offset:14336
	s_waitcnt lgkmcnt(3)
	v_mfma_f32_16x16x32_bf16 v[64:67], v[166:169], v[190:193], v[64:67]
	v_mfma_f32_16x16x32_bf16 v[68:71], v[166:169], v[194:197], v[68:71]
	v_mfma_f32_16x16x32_bf16 v[72:75], v[166:169], v[198:201], v[72:75]
	v_mfma_f32_16x16x32_bf16 v[76:79], v[166:169], v[202:205], v[76:79]
	ds_read_b128 v[166:169], v139
	s_waitcnt lgkmcnt(3)
	v_mfma_f32_16x16x32_bf16 v[80:83], v[170:173], v[190:193], v[80:83]
	v_mfma_f32_16x16x32_bf16 v[84:87], v[170:173], v[194:197], v[84:87]
	v_mfma_f32_16x16x32_bf16 v[88:91], v[170:173], v[198:201], v[88:91]
	v_mfma_f32_16x16x32_bf16 v[92:95], v[170:173], v[202:205], v[92:95]
	ds_read_b128 v[170:173], v139 offset:2048
	s_waitcnt lgkmcnt(3)
	v_mfma_f32_16x16x32_bf16 v[96:99], v[174:177], v[190:193], v[96:99]
	v_mfma_f32_16x16x32_bf16 v[100:103], v[174:177], v[194:197], v[100:103]
	v_mfma_f32_16x16x32_bf16 v[104:107], v[174:177], v[198:201], v[104:107]
	v_mfma_f32_16x16x32_bf16 v[108:111], v[174:177], v[202:205], v[108:111]
	ds_read_b128 v[174:177], v139 offset:4096
	s_waitcnt lgkmcnt(3)
	v_mfma_f32_16x16x32_bf16 v[112:115], v[182:185], v[190:193], v[112:115]
	v_mfma_f32_16x16x32_bf16 v[116:119], v[182:185], v[194:197], v[116:119]
	v_mfma_f32_16x16x32_bf16 v[120:123], v[182:185], v[198:201], v[120:123]
	v_mfma_f32_16x16x32_bf16 v[124:127], v[182:185], v[202:205], v[124:127]
	ds_read_b128 v[182:185], v139 offset:6144
	s_waitcnt lgkmcnt(3)
	v_mfma_f32_16x16x32_bf16 v[0:3], v[166:169], v[206:209], v[0:3]
	v_mfma_f32_16x16x32_bf16 v[4:7], v[166:169], v[220:223], v[4:7]
	v_mfma_f32_16x16x32_bf16 v[8:11], v[166:169], v[224:227], v[8:11]
	v_mfma_f32_16x16x32_bf16 v[12:15], v[166:169], v[228:231], v[12:15]
	ds_read_b128 v[166:169], v139 offset:8192
	s_waitcnt lgkmcnt(3)
	v_mfma_f32_16x16x32_bf16 v[16:19], v[170:173], v[206:209], v[16:19]
	v_mfma_f32_16x16x32_bf16 v[20:23], v[170:173], v[220:223], v[20:23]
	v_mfma_f32_16x16x32_bf16 v[24:27], v[170:173], v[224:227], v[24:27]
	v_mfma_f32_16x16x32_bf16 v[28:31], v[170:173], v[228:231], v[28:31]
	ds_read_b128 v[170:173], v139 offset:10240
	s_waitcnt lgkmcnt(3)
	v_mfma_f32_16x16x32_bf16 v[32:35], v[174:177], v[206:209], v[32:35]
	v_mfma_f32_16x16x32_bf16 v[36:39], v[174:177], v[220:223], v[36:39]
	v_mfma_f32_16x16x32_bf16 v[40:43], v[174:177], v[224:227], v[40:43]
	v_mfma_f32_16x16x32_bf16 v[44:47], v[174:177], v[228:231], v[44:47]
	ds_read_b128 v[174:177], v139 offset:12288
	s_waitcnt lgkmcnt(3)
	v_mfma_f32_16x16x32_bf16 v[48:51], v[182:185], v[206:209], v[48:51]
	v_mfma_f32_16x16x32_bf16 v[52:55], v[182:185], v[220:223], v[52:55]
	v_mfma_f32_16x16x32_bf16 v[56:59], v[182:185], v[224:227], v[56:59]
	v_mfma_f32_16x16x32_bf16 v[60:63], v[182:185], v[228:231], v[60:63]
	ds_read_b128 v[182:185], v139 offset:14336
	s_waitcnt lgkmcnt(3)
	v_mfma_f32_16x16x32_bf16 v[64:67], v[166:169], v[206:209], v[64:67]
	v_mfma_f32_16x16x32_bf16 v[68:71], v[166:169], v[220:223], v[68:71]
	v_mfma_f32_16x16x32_bf16 v[72:75], v[166:169], v[224:227], v[72:75]
	v_mfma_f32_16x16x32_bf16 v[76:79], v[166:169], v[228:231], v[76:79]
	s_waitcnt lgkmcnt(2)
	v_mfma_f32_16x16x32_bf16 v[80:83], v[170:173], v[206:209], v[80:83]
	v_mfma_f32_16x16x32_bf16 v[84:87], v[170:173], v[220:223], v[84:87]
	v_mfma_f32_16x16x32_bf16 v[88:91], v[170:173], v[224:227], v[88:91]
	v_mfma_f32_16x16x32_bf16 v[92:95], v[170:173], v[228:231], v[92:95]
	s_waitcnt lgkmcnt(1)
	v_mfma_f32_16x16x32_bf16 v[96:99], v[174:177], v[206:209], v[96:99]
	v_mfma_f32_16x16x32_bf16 v[100:103], v[174:177], v[220:223], v[100:103]
	v_mfma_f32_16x16x32_bf16 v[104:107], v[174:177], v[224:227], v[104:107]
	v_mfma_f32_16x16x32_bf16 v[108:111], v[174:177], v[228:231], v[108:111]
	s_waitcnt lgkmcnt(0)
	v_mfma_f32_16x16x32_bf16 v[112:115], v[182:185], v[206:209], v[112:115]
	v_mfma_f32_16x16x32_bf16 v[116:119], v[182:185], v[220:223], v[116:119]
	v_mfma_f32_16x16x32_bf16 v[120:123], v[182:185], v[224:227], v[120:123]
	v_mfma_f32_16x16x32_bf16 v[124:127], v[182:185], v[228:231], v[124:127]
	s_setprio 0
	v_xor_b32_e32 v138, 0x8000, v138
	v_xor_b32_e32 v139, 0x8000, v139
	s_xor_b32 s15, s15, 0x8000
	s_add_i32 s14, s14, 1
	s_cmp_eq_u32 s14, 16
	s_cbranch_scc0 .Lg_ph8_top
	s_waitcnt vmcnt(0)
	v_mov_b32_e32 v128, v180
	v_add_u32_e32 v193, 0x400, v153
	v_add_u32_e32 v192, 0x1000, v153
	v_add_u32_e32 v191, 0x1400, v153
	v_add_u32_e32 v190, 0x2000, v153
	v_add_u32_e32 v183, 0x2400, v153
	v_add_u32_e32 v184, 0x3000, v153
	v_add_u32_e32 v185, 0x3200, v153
	v_add_u32_e32 v186, 0x3400, v153
	v_add_u32_e32 v187, 0x3600, v153
	v_add_u32_e32 v189, 0x4000, v153
	v_add_u32_e32 v179, 0x4400, v153
	v_add_u32_e32 v181, 0x4800, v153
	v_add_u32_e32 v182, 0x5000, v153
	v_add_u32_e32 v176, 0x5400, v153
	v_add_u32_e32 v177, 0x5800, v153
	v_add_u32_e32 v178, 0x6000, v153
	v_add_u32_e32 v170, 0x6400, v153
	v_add_u32_e32 v171, 0x6800, v153
	v_add_u32_e32 v172, 0x7200, v153
	v_add_u32_e32 v173, 0x7400, v153
	v_add_u32_e32 v174, 0x7600, v153
	v_add_u32_e32 v175, 0x7800, v153
	v_add_u32_e32 v169, 0x8400, v153
	v_add_u32_e32 v168, 0x8800, v153
	v_add_u32_e32 v167, 0x9400, v153
	v_add_u32_e32 v166, 0x9800, v153
	v_add_u32_e32 v145, 0xa400, v153
	v_add_u32_e32 v140, 0xa800, v153
	v_add_u32_e32 v141, 0xb400, v153
	v_add_u32_e32 v142, 0xb600, v153
	v_add_u32_e32 v143, 0xb800, v153
	v_add_u32_e32 v144, 0xba00, v153
	s_waitcnt vmcnt(0)
	s_barrier
	s_and_saveexec_b64 s[14:15], s[6:7]
	s_cbranch_execz .LBB0_959
	v_and_b32_e32 v254, 63, v180
	v_lshrrev_b32_e32 v253, 4, v254
	v_mul_u32_u24_e32 v253, 0x840, v253
	v_and_b32_e32 v254, 15, v254
	v_lshl_add_u32 v253, v254, 2, v253
	v_and_b32_e32 v254, 64, v180
	v_lshl_add_u32 v253, v254, 2, v253
	ds_write_b32 v253, v0 offset:0
	ds_write_b32 v253, v1 offset:528
	ds_write_b32 v253, v2 offset:1056
	ds_write_b32 v253, v3 offset:1584
	ds_write_b32 v253, v4 offset:64
	ds_write_b32 v253, v5 offset:592
	ds_write_b32 v253, v6 offset:1120
	ds_write_b32 v253, v7 offset:1648
	ds_write_b32 v253, v8 offset:128
	ds_write_b32 v253, v9 offset:656
	ds_write_b32 v253, v10 offset:1184
	ds_write_b32 v253, v11 offset:1712
	ds_write_b32 v253, v12 offset:192
	ds_write_b32 v253, v13 offset:720
	ds_write_b32 v253, v14 offset:1248
	ds_write_b32 v253, v15 offset:1776
	ds_write_b32 v253, v16 offset:8448
	ds_write_b32 v253, v17 offset:8976
	ds_write_b32 v253, v18 offset:9504
	ds_write_b32 v253, v19 offset:10032
	ds_write_b32 v253, v20 offset:8512
	ds_write_b32 v253, v21 offset:9040
	ds_write_b32 v253, v22 offset:9568
	ds_write_b32 v253, v23 offset:10096
	ds_write_b32 v253, v24 offset:8576
	ds_write_b32 v253, v25 offset:9104
	ds_write_b32 v253, v26 offset:9632
	ds_write_b32 v253, v27 offset:10160
	ds_write_b32 v253, v28 offset:8640
	ds_write_b32 v253, v29 offset:9168
	ds_write_b32 v253, v30 offset:9696
	ds_write_b32 v253, v31 offset:10224
	ds_write_b32 v253, v32 offset:16896
	ds_write_b32 v253, v33 offset:17424
	ds_write_b32 v253, v34 offset:17952
	ds_write_b32 v253, v35 offset:18480
	ds_write_b32 v253, v36 offset:16960
	ds_write_b32 v253, v37 offset:17488
	ds_write_b32 v253, v38 offset:18016
	ds_write_b32 v253, v39 offset:18544
	ds_write_b32 v253, v40 offset:17024
	ds_write_b32 v253, v41 offset:17552
	ds_write_b32 v253, v42 offset:18080
	ds_write_b32 v253, v43 offset:18608
	ds_write_b32 v253, v44 offset:17088
	ds_write_b32 v253, v45 offset:17616
	ds_write_b32 v253, v46 offset:18144
	ds_write_b32 v253, v47 offset:18672
	ds_write_b32 v253, v48 offset:25344
	ds_write_b32 v253, v49 offset:25872
	ds_write_b32 v253, v50 offset:26400
	ds_write_b32 v253, v51 offset:26928
	ds_write_b32 v253, v52 offset:25408
	ds_write_b32 v253, v53 offset:25936
	ds_write_b32 v253, v54 offset:26464
	ds_write_b32 v253, v55 offset:26992
	ds_write_b32 v253, v56 offset:25472
	ds_write_b32 v253, v57 offset:26000
	ds_write_b32 v253, v58 offset:26528
	ds_write_b32 v253, v59 offset:27056
	ds_write_b32 v253, v60 offset:25536
	ds_write_b32 v253, v61 offset:26064
	ds_write_b32 v253, v62 offset:26592
	ds_write_b32 v253, v63 offset:27120
	ds_write_b32 v253, v64 offset:33792
	ds_write_b32 v253, v65 offset:34320
	ds_write_b32 v253, v66 offset:34848
	ds_write_b32 v253, v67 offset:35376
	ds_write_b32 v253, v68 offset:33856
	ds_write_b32 v253, v69 offset:34384
	ds_write_b32 v253, v70 offset:34912
	ds_write_b32 v253, v71 offset:35440
	ds_write_b32 v253, v72 offset:33920
	ds_write_b32 v253, v73 offset:34448
	ds_write_b32 v253, v74 offset:34976
	ds_write_b32 v253, v75 offset:35504
	ds_write_b32 v253, v76 offset:33984
	ds_write_b32 v253, v77 offset:34512
	ds_write_b32 v253, v78 offset:35040
	ds_write_b32 v253, v79 offset:35568
	ds_write_b32 v253, v80 offset:42240
	ds_write_b32 v253, v81 offset:42768
	ds_write_b32 v253, v82 offset:43296
	ds_write_b32 v253, v83 offset:43824
	ds_write_b32 v253, v84 offset:42304
	ds_write_b32 v253, v85 offset:42832
	ds_write_b32 v253, v86 offset:43360
	ds_write_b32 v253, v87 offset:43888
	ds_write_b32 v253, v88 offset:42368
	ds_write_b32 v253, v89 offset:42896
	ds_write_b32 v253, v90 offset:43424
	ds_write_b32 v253, v91 offset:43952
	ds_write_b32 v253, v92 offset:42432
	ds_write_b32 v253, v93 offset:42960
	ds_write_b32 v253, v94 offset:43488
	ds_write_b32 v253, v95 offset:44016
	ds_write_b32 v253, v96 offset:50688
	ds_write_b32 v253, v97 offset:51216
	ds_write_b32 v253, v98 offset:51744
	ds_write_b32 v253, v99 offset:52272
	ds_write_b32 v253, v100 offset:50752
	ds_write_b32 v253, v101 offset:51280
	ds_write_b32 v253, v102 offset:51808
	ds_write_b32 v253, v103 offset:52336
	ds_write_b32 v253, v104 offset:50816
	ds_write_b32 v253, v105 offset:51344
	ds_write_b32 v253, v106 offset:51872
	ds_write_b32 v253, v107 offset:52400
	ds_write_b32 v253, v108 offset:50880
	ds_write_b32 v253, v109 offset:51408
	ds_write_b32 v253, v110 offset:51936
	ds_write_b32 v253, v111 offset:52464
	ds_write_b32 v253, v112 offset:59136
	ds_write_b32 v253, v113 offset:59664
	ds_write_b32 v253, v114 offset:60192
	ds_write_b32 v253, v115 offset:60720
	ds_write_b32 v253, v116 offset:59200
	ds_write_b32 v253, v117 offset:59728
	ds_write_b32 v253, v118 offset:60256
	ds_write_b32 v253, v119 offset:60784
	ds_write_b32 v253, v120 offset:59264
	ds_write_b32 v253, v121 offset:59792
	ds_write_b32 v253, v122 offset:60320
	ds_write_b32 v253, v123 offset:60848
	ds_write_b32 v253, v124 offset:59328
	ds_write_b32 v253, v125 offset:59856
	ds_write_b32 v253, v126 offset:60384
	ds_write_b32 v253, v127 offset:60912

.Lg_ph9_noB:
	s_setprio 1
	s_waitcnt lgkmcnt(3)
	v_mfma_f32_16x16x32_bf16 v[0:3], v[148:151], v[194:197], v[0:3]
	v_mfma_f32_16x16x32_bf16 v[4:7], v[148:151], v[198:201], v[4:7]
	v_mfma_f32_16x16x32_bf16 v[8:11], v[148:151], v[202:205], v[8:11]
	v_mfma_f32_16x16x32_bf16 v[12:15], v[148:151], v[206:209], v[12:15]
	ds_read_b128 v[148:151], v138 offset:8192
	s_waitcnt lgkmcnt(3)
	v_mfma_f32_16x16x32_bf16 v[16:19], v[174:177], v[194:197], v[16:19]
	v_mfma_f32_16x16x32_bf16 v[20:23], v[174:177], v[198:201], v[20:23]
	v_mfma_f32_16x16x32_bf16 v[24:27], v[174:177], v[202:205], v[24:27]
	v_mfma_f32_16x16x32_bf16 v[28:31], v[174:177], v[206:209], v[28:31]
	ds_read_b128 v[174:177], v138 offset:10240
	s_waitcnt lgkmcnt(3)
	v_mfma_f32_16x16x32_bf16 v[32:35], v[182:185], v[194:197], v[32:35]
	v_mfma_f32_16x16x32_bf16 v[36:39], v[182:185], v[198:201], v[36:39]
	v_mfma_f32_16x16x32_bf16 v[40:43], v[182:185], v[202:205], v[40:43]
	v_mfma_f32_16x16x32_bf16 v[44:47], v[182:185], v[206:209], v[44:47]
	ds_read_b128 v[182:185], v138 offset:12288
	s_waitcnt lgkmcnt(3)
	v_mfma_f32_16x16x32_bf16 v[48:51], v[190:193], v[194:197], v[48:51]
	v_mfma_f32_16x16x32_bf16 v[52:55], v[190:193], v[198:201], v[52:55]
	v_mfma_f32_16x16x32_bf16 v[56:59], v[190:193], v[202:205], v[56:59]
	v_mfma_f32_16x16x32_bf16 v[60:63], v[190:193], v[206:209], v[60:63]
	ds_read_b128 v[190:193], v138 offset:14336
	s_waitcnt lgkmcnt(3)
	v_mfma_f32_16x16x32_bf16 v[64:67], v[148:151], v[194:197], v[64:67]
	v_mfma_f32_16x16x32_bf16 v[68:71], v[148:151], v[198:201], v[68:71]
	v_mfma_f32_16x16x32_bf16 v[72:75], v[148:151], v[202:205], v[72:75]
	v_mfma_f32_16x16x32_bf16 v[76:79], v[148:151], v[206:209], v[76:79]
	ds_read_b128 v[148:151], v139
	s_waitcnt lgkmcnt(3)
	v_mfma_f32_16x16x32_bf16 v[80:83], v[174:177], v[194:197], v[80:83]
	v_mfma_f32_16x16x32_bf16 v[84:87], v[174:177], v[198:201], v[84:87]
	v_mfma_f32_16x16x32_bf16 v[88:91], v[174:177], v[202:205], v[88:91]
	v_mfma_f32_16x16x32_bf16 v[92:95], v[174:177], v[206:209], v[92:95]
	ds_read_b128 v[174:177], v139 offset:2048
	s_waitcnt lgkmcnt(3)
	v_mfma_f32_16x16x32_bf16 v[96:99], v[182:185], v[194:197], v[96:99]
	v_mfma_f32_16x16x32_bf16 v[100:103], v[182:185], v[198:201], v[100:103]
	v_mfma_f32_16x16x32_bf16 v[104:107], v[182:185], v[202:205], v[104:107]
	v_mfma_f32_16x16x32_bf16 v[108:111], v[182:185], v[206:209], v[108:111]
	ds_read_b128 v[182:185], v139 offset:4096
	s_waitcnt lgkmcnt(3)
	v_mfma_f32_16x16x32_bf16 v[112:115], v[190:193], v[194:197], v[112:115]
	v_mfma_f32_16x16x32_bf16 v[116:119], v[190:193], v[198:201], v[116:119]
	v_mfma_f32_16x16x32_bf16 v[120:123], v[190:193], v[202:205], v[120:123]
	v_mfma_f32_16x16x32_bf16 v[124:127], v[190:193], v[206:209], v[124:127]
	ds_read_b128 v[190:193], v139 offset:6144
	s_waitcnt lgkmcnt(3)
	v_mfma_f32_16x16x32_bf16 v[0:3], v[148:151], v[214:217], v[0:3]
	v_mfma_f32_16x16x32_bf16 v[4:7], v[148:151], v[226:229], v[4:7]
	v_mfma_f32_16x16x32_bf16 v[8:11], v[148:151], v[230:233], v[8:11]
	v_mfma_f32_16x16x32_bf16 v[12:15], v[148:151], v[234:237], v[12:15]
	ds_read_b128 v[148:151], v139 offset:8192
	s_waitcnt lgkmcnt(3)
	v_mfma_f32_16x16x32_bf16 v[16:19], v[174:177], v[214:217], v[16:19]
	v_mfma_f32_16x16x32_bf16 v[20:23], v[174:177], v[226:229], v[20:23]
	v_mfma_f32_16x16x32_bf16 v[24:27], v[174:177], v[230:233], v[24:27]
	v_mfma_f32_16x16x32_bf16 v[28:31], v[174:177], v[234:237], v[28:31]
	ds_read_b128 v[174:177], v139 offset:10240
	s_waitcnt lgkmcnt(3)
	v_mfma_f32_16x16x32_bf16 v[32:35], v[182:185], v[214:217], v[32:35]
	v_mfma_f32_16x16x32_bf16 v[36:39], v[182:185], v[226:229], v[36:39]
	v_mfma_f32_16x16x32_bf16 v[40:43], v[182:185], v[230:233], v[40:43]
	v_mfma_f32_16x16x32_bf16 v[44:47], v[182:185], v[234:237], v[44:47]
	ds_read_b128 v[182:185], v139 offset:12288
	s_waitcnt lgkmcnt(3)
	v_mfma_f32_16x16x32_bf16 v[48:51], v[190:193], v[214:217], v[48:51]
	v_mfma_f32_16x16x32_bf16 v[52:55], v[190:193], v[226:229], v[52:55]
	v_mfma_f32_16x16x32_bf16 v[56:59], v[190:193], v[230:233], v[56:59]
	v_mfma_f32_16x16x32_bf16 v[60:63], v[190:193], v[234:237], v[60:63]
	ds_read_b128 v[190:193], v139 offset:14336
	s_waitcnt lgkmcnt(3)
	v_mfma_f32_16x16x32_bf16 v[64:67], v[148:151], v[214:217], v[64:67]
	v_mfma_f32_16x16x32_bf16 v[68:71], v[148:151], v[226:229], v[68:71]
	v_mfma_f32_16x16x32_bf16 v[72:75], v[148:151], v[230:233], v[72:75]
	v_mfma_f32_16x16x32_bf16 v[76:79], v[148:151], v[234:237], v[76:79]
	s_waitcnt lgkmcnt(2)
	v_mfma_f32_16x16x32_bf16 v[80:83], v[174:177], v[214:217], v[80:83]
	v_mfma_f32_16x16x32_bf16 v[84:87], v[174:177], v[226:229], v[84:87]
	v_mfma_f32_16x16x32_bf16 v[88:91], v[174:177], v[230:233], v[88:91]
	v_mfma_f32_16x16x32_bf16 v[92:95], v[174:177], v[234:237], v[92:95]
	s_waitcnt lgkmcnt(1)
	v_mfma_f32_16x16x32_bf16 v[96:99], v[182:185], v[214:217], v[96:99]
	v_mfma_f32_16x16x32_bf16 v[100:103], v[182:185], v[226:229], v[100:103]
	v_mfma_f32_16x16x32_bf16 v[104:107], v[182:185], v[230:233], v[104:107]
	v_mfma_f32_16x16x32_bf16 v[108:111], v[182:185], v[234:237], v[108:111]
	s_waitcnt lgkmcnt(0)
	v_mfma_f32_16x16x32_bf16 v[112:115], v[190:193], v[214:217], v[112:115]
	v_mfma_f32_16x16x32_bf16 v[116:119], v[190:193], v[226:229], v[116:119]
	v_mfma_f32_16x16x32_bf16 v[120:123], v[190:193], v[230:233], v[120:123]
	v_mfma_f32_16x16x32_bf16 v[124:127], v[190:193], v[234:237], v[124:127]
	s_setprio 0
	v_xor_b32_e32 v138, 0x8000, v138
	v_xor_b32_e32 v139, 0x8000, v139
	s_xor_b32 s17, s17, 0x8000
	s_add_i32 s16, s16, 1
	s_cmp_eq_u32 s16, 16
	s_cbranch_scc0 .Lg_ph9_top
	s_waitcnt vmcnt(0)
	v_mov_b32_e32 v146, v180
	v_add_u32_e32 v209, 0x400, v157
	v_add_u32_e32 v208, 0x1000, v157
	v_add_u32_e32 v207, 0x1400, v157
	v_add_u32_e32 v206, 0x2000, v157
	v_add_u32_e32 v200, 0x2400, v157
	v_add_u32_e32 v201, 0x3000, v157
	v_add_u32_e32 v202, 0x3200, v157
	v_add_u32_e32 v203, 0x3400, v157
	v_add_u32_e32 v204, 0x3600, v157
	v_add_u32_e32 v205, 0x4000, v157
	v_add_u32_e32 v197, 0x4400, v157
	v_add_u32_e32 v198, 0x4800, v157
	v_add_u32_e32 v199, 0x5000, v157
	v_add_u32_e32 v194, 0x5400, v157
	v_add_u32_e32 v195, 0x5800, v157
	v_add_u32_e32 v196, 0x6000, v157
	v_add_u32_e32 v187, 0x6400, v157
	v_add_u32_e32 v189, 0x6800, v157
	v_add_u32_e32 v190, 0x7200, v157
	v_add_u32_e32 v191, 0x7400, v157
	v_add_u32_e32 v192, 0x7600, v157
	v_add_u32_e32 v193, 0x7800, v157
	v_add_u32_e32 v186, 0x8400, v157
	v_add_u32_e32 v185, 0x8800, v157
	v_add_u32_e32 v184, 0x9400, v157
	v_add_u32_e32 v183, 0x9800, v157
	v_add_u32_e32 v181, 0xa400, v157
	v_add_u32_e32 v174, 0xa800, v157
	v_add_u32_e32 v175, 0xb400, v157
	v_add_u32_e32 v176, 0xb600, v157
	v_add_u32_e32 v177, 0xb800, v157
	v_add_u32_e32 v178, 0xba00, v157
	s_waitcnt vmcnt(0)
	s_barrier
	s_and_saveexec_b64 s[16:17], s[6:7]
	s_cbranch_execz .LBB0_1025
	v_and_b32_e32 v254, 63, v180
	v_lshrrev_b32_e32 v253, 4, v254
	v_mul_u32_u24_e32 v253, 0x840, v253
	v_and_b32_e32 v254, 15, v254
	v_lshl_add_u32 v253, v254, 2, v253
	v_and_b32_e32 v254, 64, v180
	v_lshl_add_u32 v253, v254, 2, v253
	ds_write_b32 v253, v0 offset:0
	ds_write_b32 v253, v1 offset:528
	ds_write_b32 v253, v2 offset:1056
	ds_write_b32 v253, v3 offset:1584
	ds_write_b32 v253, v4 offset:64
	ds_write_b32 v253, v5 offset:592
	ds_write_b32 v253, v6 offset:1120
	ds_write_b32 v253, v7 offset:1648
	ds_write_b32 v253, v8 offset:128
	ds_write_b32 v253, v9 offset:656
	ds_write_b32 v253, v10 offset:1184
	ds_write_b32 v253, v11 offset:1712
	ds_write_b32 v253, v12 offset:192
	ds_write_b32 v253, v13 offset:720
	ds_write_b32 v253, v14 offset:1248
	ds_write_b32 v253, v15 offset:1776
	ds_write_b32 v253, v16 offset:8448
	ds_write_b32 v253, v17 offset:8976
	ds_write_b32 v253, v18 offset:9504
	ds_write_b32 v253, v19 offset:10032
	ds_write_b32 v253, v20 offset:8512
	ds_write_b32 v253, v21 offset:9040
	ds_write_b32 v253, v22 offset:9568
	ds_write_b32 v253, v23 offset:10096
	ds_write_b32 v253, v24 offset:8576
	ds_write_b32 v253, v25 offset:9104
	ds_write_b32 v253, v26 offset:9632
	ds_write_b32 v253, v27 offset:10160
	ds_write_b32 v253, v28 offset:8640
	ds_write_b32 v253, v29 offset:9168
	ds_write_b32 v253, v30 offset:9696
	ds_write_b32 v253, v31 offset:10224
	ds_write_b32 v253, v32 offset:16896
	ds_write_b32 v253, v33 offset:17424
	ds_write_b32 v253, v34 offset:17952
	ds_write_b32 v253, v35 offset:18480
	ds_write_b32 v253, v36 offset:16960
	ds_write_b32 v253, v37 offset:17488
	ds_write_b32 v253, v38 offset:18016
	ds_write_b32 v253, v39 offset:18544
	ds_write_b32 v253, v40 offset:17024
	ds_write_b32 v253, v41 offset:17552
	ds_write_b32 v253, v42 offset:18080
	ds_write_b32 v253, v43 offset:18608
	ds_write_b32 v253, v44 offset:17088
	ds_write_b32 v253, v45 offset:17616
	ds_write_b32 v253, v46 offset:18144
	ds_write_b32 v253, v47 offset:18672
	ds_write_b32 v253, v48 offset:25344
	ds_write_b32 v253, v49 offset:25872
	ds_write_b32 v253, v50 offset:26400
	ds_write_b32 v253, v51 offset:26928
	ds_write_b32 v253, v52 offset:25408
	ds_write_b32 v253, v53 offset:25936
	ds_write_b32 v253, v54 offset:26464
	ds_write_b32 v253, v55 offset:26992
	ds_write_b32 v253, v56 offset:25472
	ds_write_b32 v253, v57 offset:26000
	ds_write_b32 v253, v58 offset:26528
	ds_write_b32 v253, v59 offset:27056
	ds_write_b32 v253, v60 offset:25536
	ds_write_b32 v253, v61 offset:26064
	ds_write_b32 v253, v62 offset:26592
	ds_write_b32 v253, v63 offset:27120
	ds_write_b32 v253, v64 offset:33792
	ds_write_b32 v253, v65 offset:34320
	ds_write_b32 v253, v66 offset:34848
	ds_write_b32 v253, v67 offset:35376
	ds_write_b32 v253, v68 offset:33856
	ds_write_b32 v253, v69 offset:34384
	ds_write_b32 v253, v70 offset:34912
	ds_write_b32 v253, v71 offset:35440
	ds_write_b32 v253, v72 offset:33920
	ds_write_b32 v253, v73 offset:34448
	ds_write_b32 v253, v74 offset:34976
	ds_write_b32 v253, v75 offset:35504
	ds_write_b32 v253, v76 offset:33984
	ds_write_b32 v253, v77 offset:34512
	ds_write_b32 v253, v78 offset:35040
	ds_write_b32 v253, v79 offset:35568
	ds_write_b32 v253, v80 offset:42240
	ds_write_b32 v253, v81 offset:42768
	ds_write_b32 v253, v82 offset:43296
	ds_write_b32 v253, v83 offset:43824
	ds_write_b32 v253, v84 offset:42304
	ds_write_b32 v253, v85 offset:42832
	ds_write_b32 v253, v86 offset:43360
	ds_write_b32 v253, v87 offset:43888
	ds_write_b32 v253, v88 offset:42368
	ds_write_b32 v253, v89 offset:42896
	ds_write_b32 v253, v90 offset:43424
	ds_write_b32 v253, v91 offset:43952
	ds_write_b32 v253, v92 offset:42432
	ds_write_b32 v253, v93 offset:42960
	ds_write_b32 v253, v94 offset:43488
	ds_write_b32 v253, v95 offset:44016
	ds_write_b32 v253, v96 offset:50688
	ds_write_b32 v253, v97 offset:51216
	ds_write_b32 v253, v98 offset:51744
	ds_write_b32 v253, v99 offset:52272
	ds_write_b32 v253, v100 offset:50752
	ds_write_b32 v253, v101 offset:51280
	ds_write_b32 v253, v102 offset:51808
	ds_write_b32 v253, v103 offset:52336
	ds_write_b32 v253, v104 offset:50816
	ds_write_b32 v253, v105 offset:51344
	ds_write_b32 v253, v106 offset:51872
	ds_write_b32 v253, v107 offset:52400
	ds_write_b32 v253, v108 offset:50880
	ds_write_b32 v253, v109 offset:51408
	ds_write_b32 v253, v110 offset:51936
	ds_write_b32 v253, v111 offset:52464
	ds_write_b32 v253, v112 offset:59136
	ds_write_b32 v253, v113 offset:59664
	ds_write_b32 v253, v114 offset:60192
	ds_write_b32 v253, v115 offset:60720
	ds_write_b32 v253, v116 offset:59200
	ds_write_b32 v253, v117 offset:59728
	ds_write_b32 v253, v118 offset:60256
	ds_write_b32 v253, v119 offset:60784
	ds_write_b32 v253, v120 offset:59264
	ds_write_b32 v253, v121 offset:59792
	ds_write_b32 v253, v122 offset:60320
	ds_write_b32 v253, v123 offset:60848
	ds_write_b32 v253, v124 offset:59328
	ds_write_b32 v253, v125 offset:59856
	ds_write_b32 v253, v126 offset:60384
	ds_write_b32 v253, v127 offset:60912

.Lg_ph11a_noB:
	s_setprio 1
	s_waitcnt lgkmcnt(3)
	v_mfma_f32_16x16x32_bf16 v[0:3], v[156:159], v[198:201], v[0:3]
	v_mfma_f32_16x16x32_bf16 v[4:7], v[156:159], v[202:205], v[4:7]
	v_mfma_f32_16x16x32_bf16 v[8:11], v[156:159], v[206:209], v[8:11]
	v_mfma_f32_16x16x32_bf16 v[12:15], v[156:159], v[214:217], v[12:15]
	ds_read_b128 v[156:159], v136 offset:8192
	s_waitcnt lgkmcnt(3)
	v_mfma_f32_16x16x32_bf16 v[16:19], v[182:185], v[198:201], v[16:19]
	v_mfma_f32_16x16x32_bf16 v[20:23], v[182:185], v[202:205], v[20:23]
	v_mfma_f32_16x16x32_bf16 v[24:27], v[182:185], v[206:209], v[24:27]
	v_mfma_f32_16x16x32_bf16 v[28:31], v[182:185], v[214:217], v[28:31]
	ds_read_b128 v[182:185], v136 offset:10240
	s_waitcnt lgkmcnt(3)
	v_mfma_f32_16x16x32_bf16 v[32:35], v[190:193], v[198:201], v[32:35]
	v_mfma_f32_16x16x32_bf16 v[36:39], v[190:193], v[202:205], v[36:39]
	v_mfma_f32_16x16x32_bf16 v[40:43], v[190:193], v[206:209], v[40:43]
	v_mfma_f32_16x16x32_bf16 v[44:47], v[190:193], v[214:217], v[44:47]
	ds_read_b128 v[190:193], v136 offset:12288
	s_waitcnt lgkmcnt(3)
	v_mfma_f32_16x16x32_bf16 v[48:51], v[194:197], v[198:201], v[48:51]
	v_mfma_f32_16x16x32_bf16 v[52:55], v[194:197], v[202:205], v[52:55]
	v_mfma_f32_16x16x32_bf16 v[56:59], v[194:197], v[206:209], v[56:59]
	v_mfma_f32_16x16x32_bf16 v[60:63], v[194:197], v[214:217], v[60:63]
	ds_read_b128 v[194:197], v136 offset:14336
	s_waitcnt lgkmcnt(3)
	v_mfma_f32_16x16x32_bf16 v[64:67], v[156:159], v[198:201], v[64:67]
	v_mfma_f32_16x16x32_bf16 v[68:71], v[156:159], v[202:205], v[68:71]
	v_mfma_f32_16x16x32_bf16 v[72:75], v[156:159], v[206:209], v[72:75]
	v_mfma_f32_16x16x32_bf16 v[76:79], v[156:159], v[214:217], v[76:79]
	ds_read_b128 v[156:159], v137
	s_waitcnt lgkmcnt(3)
	v_mfma_f32_16x16x32_bf16 v[80:83], v[182:185], v[198:201], v[80:83]
	v_mfma_f32_16x16x32_bf16 v[84:87], v[182:185], v[202:205], v[84:87]
	v_mfma_f32_16x16x32_bf16 v[88:91], v[182:185], v[206:209], v[88:91]
	v_mfma_f32_16x16x32_bf16 v[92:95], v[182:185], v[214:217], v[92:95]
	ds_read_b128 v[182:185], v137 offset:2048
	s_waitcnt lgkmcnt(3)
	v_mfma_f32_16x16x32_bf16 v[96:99], v[190:193], v[198:201], v[96:99]
	v_mfma_f32_16x16x32_bf16 v[100:103], v[190:193], v[202:205], v[100:103]
	v_mfma_f32_16x16x32_bf16 v[104:107], v[190:193], v[206:209], v[104:107]
	v_mfma_f32_16x16x32_bf16 v[108:111], v[190:193], v[214:217], v[108:111]
	ds_read_b128 v[190:193], v137 offset:4096
	s_waitcnt lgkmcnt(3)
	v_mfma_f32_16x16x32_bf16 v[112:115], v[194:197], v[198:201], v[112:115]
	v_mfma_f32_16x16x32_bf16 v[116:119], v[194:197], v[202:205], v[116:119]
	v_mfma_f32_16x16x32_bf16 v[120:123], v[194:197], v[206:209], v[120:123]
	v_mfma_f32_16x16x32_bf16 v[124:127], v[194:197], v[214:217], v[124:127]
	ds_read_b128 v[194:197], v137 offset:6144
	s_waitcnt lgkmcnt(3)
	v_mfma_f32_16x16x32_bf16 v[0:3], v[156:159], v[218:221], v[0:3]
	v_mfma_f32_16x16x32_bf16 v[4:7], v[156:159], v[222:225], v[4:7]
	v_mfma_f32_16x16x32_bf16 v[8:11], v[156:159], v[226:229], v[8:11]
	v_mfma_f32_16x16x32_bf16 v[12:15], v[156:159], v[230:233], v[12:15]
	ds_read_b128 v[156:159], v137 offset:8192
	s_waitcnt lgkmcnt(3)
	v_mfma_f32_16x16x32_bf16 v[16:19], v[182:185], v[218:221], v[16:19]
	v_mfma_f32_16x16x32_bf16 v[20:23], v[182:185], v[222:225], v[20:23]
	v_mfma_f32_16x16x32_bf16 v[24:27], v[182:185], v[226:229], v[24:27]
	v_mfma_f32_16x16x32_bf16 v[28:31], v[182:185], v[230:233], v[28:31]
	ds_read_b128 v[182:185], v137 offset:10240
	s_waitcnt lgkmcnt(3)
	v_mfma_f32_16x16x32_bf16 v[32:35], v[190:193], v[218:221], v[32:35]
	v_mfma_f32_16x16x32_bf16 v[36:39], v[190:193], v[222:225], v[36:39]
	v_mfma_f32_16x16x32_bf16 v[40:43], v[190:193], v[226:229], v[40:43]
	v_mfma_f32_16x16x32_bf16 v[44:47], v[190:193], v[230:233], v[44:47]
	ds_read_b128 v[190:193], v137 offset:12288
	s_waitcnt lgkmcnt(3)
	v_mfma_f32_16x16x32_bf16 v[48:51], v[194:197], v[218:221], v[48:51]
	v_mfma_f32_16x16x32_bf16 v[52:55], v[194:197], v[222:225], v[52:55]
	v_mfma_f32_16x16x32_bf16 v[56:59], v[194:197], v[226:229], v[56:59]
	v_mfma_f32_16x16x32_bf16 v[60:63], v[194:197], v[230:233], v[60:63]
	ds_read_b128 v[194:197], v137 offset:14336
	s_waitcnt lgkmcnt(3)
	v_mfma_f32_16x16x32_bf16 v[64:67], v[156:159], v[218:221], v[64:67]
	v_mfma_f32_16x16x32_bf16 v[68:71], v[156:159], v[222:225], v[68:71]
	v_mfma_f32_16x16x32_bf16 v[72:75], v[156:159], v[226:229], v[72:75]
	v_mfma_f32_16x16x32_bf16 v[76:79], v[156:159], v[230:233], v[76:79]
	s_waitcnt lgkmcnt(2)
	v_mfma_f32_16x16x32_bf16 v[80:83], v[182:185], v[218:221], v[80:83]
	v_mfma_f32_16x16x32_bf16 v[84:87], v[182:185], v[222:225], v[84:87]
	v_mfma_f32_16x16x32_bf16 v[88:91], v[182:185], v[226:229], v[88:91]
	v_mfma_f32_16x16x32_bf16 v[92:95], v[182:185], v[230:233], v[92:95]
	s_waitcnt lgkmcnt(1)
	v_mfma_f32_16x16x32_bf16 v[96:99], v[190:193], v[218:221], v[96:99]
	v_mfma_f32_16x16x32_bf16 v[100:103], v[190:193], v[222:225], v[100:103]
	v_mfma_f32_16x16x32_bf16 v[104:107], v[190:193], v[226:229], v[104:107]
	v_mfma_f32_16x16x32_bf16 v[108:111], v[190:193], v[230:233], v[108:111]
	s_waitcnt lgkmcnt(0)
	v_mfma_f32_16x16x32_bf16 v[112:115], v[194:197], v[218:221], v[112:115]
	v_mfma_f32_16x16x32_bf16 v[116:119], v[194:197], v[222:225], v[116:119]
	v_mfma_f32_16x16x32_bf16 v[120:123], v[194:197], v[226:229], v[120:123]
	v_mfma_f32_16x16x32_bf16 v[124:127], v[194:197], v[230:233], v[124:127]
	s_setprio 0
	v_xor_b32_e32 v136, 0x8000, v136
	v_xor_b32_e32 v137, 0x8000, v137
	s_xor_b32 s27, s27, 0x8000
	s_add_i32 s26, s26, 1
	s_cmp_eq_u32 s26, 16
	s_cbranch_scc0 .Lg_ph11a_top
	s_waitcnt vmcnt(0)
	v_mov_b32_e32 v130, v180
	s_waitcnt vmcnt(0)
	s_barrier
	s_and_saveexec_b64 s[26:27], s[6:7]
	s_cbranch_execz .LBB0_1179
	v_and_b32_e32 v254, 63, v180
	v_lshrrev_b32_e32 v253, 4, v254
	v_mul_u32_u24_e32 v253, 0x840, v253
	v_and_b32_e32 v254, 15, v254
	v_lshl_add_u32 v253, v254, 2, v253
	v_and_b32_e32 v254, 64, v180
	v_lshl_add_u32 v253, v254, 2, v253
	ds_write_b32 v253, v0 offset:0
	ds_write_b32 v253, v1 offset:528
	ds_write_b32 v253, v2 offset:1056
	ds_write_b32 v253, v3 offset:1584
	ds_write_b32 v253, v4 offset:64
	ds_write_b32 v253, v5 offset:592
	ds_write_b32 v253, v6 offset:1120
	ds_write_b32 v253, v7 offset:1648
	ds_write_b32 v253, v8 offset:128
	ds_write_b32 v253, v9 offset:656
	ds_write_b32 v253, v10 offset:1184
	ds_write_b32 v253, v11 offset:1712
	ds_write_b32 v253, v12 offset:192
	ds_write_b32 v253, v13 offset:720
	ds_write_b32 v253, v14 offset:1248
	ds_write_b32 v253, v15 offset:1776
	ds_write_b32 v253, v16 offset:8448
	ds_write_b32 v253, v17 offset:8976
	ds_write_b32 v253, v18 offset:9504
	ds_write_b32 v253, v19 offset:10032
	ds_write_b32 v253, v20 offset:8512
	ds_write_b32 v253, v21 offset:9040
	ds_write_b32 v253, v22 offset:9568
	ds_write_b32 v253, v23 offset:10096
	ds_write_b32 v253, v24 offset:8576
	ds_write_b32 v253, v25 offset:9104
	ds_write_b32 v253, v26 offset:9632
	ds_write_b32 v253, v27 offset:10160
	ds_write_b32 v253, v28 offset:8640
	ds_write_b32 v253, v29 offset:9168
	ds_write_b32 v253, v30 offset:9696
	ds_write_b32 v253, v31 offset:10224
	ds_write_b32 v253, v32 offset:16896
	ds_write_b32 v253, v33 offset:17424
	ds_write_b32 v253, v34 offset:17952
	ds_write_b32 v253, v35 offset:18480
	ds_write_b32 v253, v36 offset:16960
	ds_write_b32 v253, v37 offset:17488
	ds_write_b32 v253, v38 offset:18016
	ds_write_b32 v253, v39 offset:18544
	ds_write_b32 v253, v40 offset:17024
	ds_write_b32 v253, v41 offset:17552
	ds_write_b32 v253, v42 offset:18080
	ds_write_b32 v253, v43 offset:18608
	ds_write_b32 v253, v44 offset:17088
	ds_write_b32 v253, v45 offset:17616
	ds_write_b32 v253, v46 offset:18144
	ds_write_b32 v253, v47 offset:18672
	ds_write_b32 v253, v48 offset:25344
	ds_write_b32 v253, v49 offset:25872
	ds_write_b32 v253, v50 offset:26400
	ds_write_b32 v253, v51 offset:26928
	ds_write_b32 v253, v52 offset:25408
	ds_write_b32 v253, v53 offset:25936
	ds_write_b32 v253, v54 offset:26464
	ds_write_b32 v253, v55 offset:26992
	ds_write_b32 v253, v56 offset:25472
	ds_write_b32 v253, v57 offset:26000
	ds_write_b32 v253, v58 offset:26528
	ds_write_b32 v253, v59 offset:27056
	ds_write_b32 v253, v60 offset:25536
	ds_write_b32 v253, v61 offset:26064
	ds_write_b32 v253, v62 offset:26592
	ds_write_b32 v253, v63 offset:27120
	ds_write_b32 v253, v64 offset:33792
	ds_write_b32 v253, v65 offset:34320
	ds_write_b32 v253, v66 offset:34848
	ds_write_b32 v253, v67 offset:35376
	ds_write_b32 v253, v68 offset:33856
	ds_write_b32 v253, v69 offset:34384
	ds_write_b32 v253, v70 offset:34912
	ds_write_b32 v253, v71 offset:35440
	ds_write_b32 v253, v72 offset:33920
	ds_write_b32 v253, v73 offset:34448
	ds_write_b32 v253, v74 offset:34976
	ds_write_b32 v253, v75 offset:35504
	ds_write_b32 v253, v76 offset:33984
	ds_write_b32 v253, v77 offset:34512
	ds_write_b32 v253, v78 offset:35040
	ds_write_b32 v253, v79 offset:35568
	ds_write_b32 v253, v80 offset:42240
	ds_write_b32 v253, v81 offset:42768
	ds_write_b32 v253, v82 offset:43296
	ds_write_b32 v253, v83 offset:43824
	ds_write_b32 v253, v84 offset:42304
	ds_write_b32 v253, v85 offset:42832
	ds_write_b32 v253, v86 offset:43360
	ds_write_b32 v253, v87 offset:43888
	ds_write_b32 v253, v88 offset:42368
	ds_write_b32 v253, v89 offset:42896
	ds_write_b32 v253, v90 offset:43424
	ds_write_b32 v253, v91 offset:43952
	ds_write_b32 v253, v92 offset:42432
	ds_write_b32 v253, v93 offset:42960
	ds_write_b32 v253, v94 offset:43488
	ds_write_b32 v253, v95 offset:44016
	ds_write_b32 v253, v96 offset:50688
	ds_write_b32 v253, v97 offset:51216
	ds_write_b32 v253, v98 offset:51744
	ds_write_b32 v253, v99 offset:52272
	ds_write_b32 v253, v100 offset:50752
	ds_write_b32 v253, v101 offset:51280
	ds_write_b32 v253, v102 offset:51808
	ds_write_b32 v253, v103 offset:52336
	ds_write_b32 v253, v104 offset:50816
	ds_write_b32 v253, v105 offset:51344
	ds_write_b32 v253, v106 offset:51872
	ds_write_b32 v253, v107 offset:52400
	ds_write_b32 v253, v108 offset:50880
	ds_write_b32 v253, v109 offset:51408
	ds_write_b32 v253, v110 offset:51936
	ds_write_b32 v253, v111 offset:52464
	ds_write_b32 v253, v112 offset:59136
	ds_write_b32 v253, v113 offset:59664
	ds_write_b32 v253, v114 offset:60192
	ds_write_b32 v253, v115 offset:60720
	ds_write_b32 v253, v116 offset:59200
	ds_write_b32 v253, v117 offset:59728
	ds_write_b32 v253, v118 offset:60256
	ds_write_b32 v253, v119 offset:60784
	ds_write_b32 v253, v120 offset:59264
	ds_write_b32 v253, v121 offset:59792
	ds_write_b32 v253, v122 offset:60320
	ds_write_b32 v253, v123 offset:60848
	ds_write_b32 v253, v124 offset:59328
	ds_write_b32 v253, v125 offset:59856
	ds_write_b32 v253, v126 offset:60384
	ds_write_b32 v253, v127 offset:60912

.Lg_ph11b_noB:
	s_setprio 1
	s_waitcnt lgkmcnt(3)
	v_mfma_f32_16x16x32_bf16 v[0:3], v[144:147], v[190:193], v[0:3]
	v_mfma_f32_16x16x32_bf16 v[4:7], v[144:147], v[194:197], v[4:7]
	v_mfma_f32_16x16x32_bf16 v[8:11], v[144:147], v[198:201], v[8:11]
	v_mfma_f32_16x16x32_bf16 v[12:15], v[144:147], v[202:205], v[12:15]
	ds_read_b128 v[144:147], v136 offset:8192
	s_waitcnt lgkmcnt(3)
	v_mfma_f32_16x16x32_bf16 v[16:19], v[148:151], v[190:193], v[16:19]
	v_mfma_f32_16x16x32_bf16 v[20:23], v[148:151], v[194:197], v[20:23]
	v_mfma_f32_16x16x32_bf16 v[24:27], v[148:151], v[198:201], v[24:27]
	v_mfma_f32_16x16x32_bf16 v[28:31], v[148:151], v[202:205], v[28:31]
	ds_read_b128 v[148:151], v136 offset:10240
	s_waitcnt lgkmcnt(3)
	v_mfma_f32_16x16x32_bf16 v[32:35], v[156:159], v[190:193], v[32:35]
	v_mfma_f32_16x16x32_bf16 v[36:39], v[156:159], v[194:197], v[36:39]
	v_mfma_f32_16x16x32_bf16 v[40:43], v[156:159], v[198:201], v[40:43]
	v_mfma_f32_16x16x32_bf16 v[44:47], v[156:159], v[202:205], v[44:47]
	ds_read_b128 v[156:159], v136 offset:12288
	s_waitcnt lgkmcnt(3)
	v_mfma_f32_16x16x32_bf16 v[48:51], v[182:185], v[190:193], v[48:51]
	v_mfma_f32_16x16x32_bf16 v[52:55], v[182:185], v[194:197], v[52:55]
	v_mfma_f32_16x16x32_bf16 v[56:59], v[182:185], v[198:201], v[56:59]
	v_mfma_f32_16x16x32_bf16 v[60:63], v[182:185], v[202:205], v[60:63]
	ds_read_b128 v[182:185], v136 offset:14336
	s_waitcnt lgkmcnt(3)
	v_mfma_f32_16x16x32_bf16 v[64:67], v[144:147], v[190:193], v[64:67]
	v_mfma_f32_16x16x32_bf16 v[68:71], v[144:147], v[194:197], v[68:71]
	v_mfma_f32_16x16x32_bf16 v[72:75], v[144:147], v[198:201], v[72:75]
	v_mfma_f32_16x16x32_bf16 v[76:79], v[144:147], v[202:205], v[76:79]
	ds_read_b128 v[144:147], v137
	s_waitcnt lgkmcnt(3)
	v_mfma_f32_16x16x32_bf16 v[80:83], v[148:151], v[190:193], v[80:83]
	v_mfma_f32_16x16x32_bf16 v[84:87], v[148:151], v[194:197], v[84:87]
	v_mfma_f32_16x16x32_bf16 v[88:91], v[148:151], v[198:201], v[88:91]
	v_mfma_f32_16x16x32_bf16 v[92:95], v[148:151], v[202:205], v[92:95]
	ds_read_b128 v[148:151], v137 offset:2048
	s_waitcnt lgkmcnt(3)
	v_mfma_f32_16x16x32_bf16 v[96:99], v[156:159], v[190:193], v[96:99]
	v_mfma_f32_16x16x32_bf16 v[100:103], v[156:159], v[194:197], v[100:103]
	v_mfma_f32_16x16x32_bf16 v[104:107], v[156:159], v[198:201], v[104:107]
	v_mfma_f32_16x16x32_bf16 v[108:111], v[156:159], v[202:205], v[108:111]
	ds_read_b128 v[156:159], v137 offset:4096
	s_waitcnt lgkmcnt(3)
	v_mfma_f32_16x16x32_bf16 v[112:115], v[182:185], v[190:193], v[112:115]
	v_mfma_f32_16x16x32_bf16 v[116:119], v[182:185], v[194:197], v[116:119]
	v_mfma_f32_16x16x32_bf16 v[120:123], v[182:185], v[198:201], v[120:123]
	v_mfma_f32_16x16x32_bf16 v[124:127], v[182:185], v[202:205], v[124:127]
	ds_read_b128 v[182:185], v137 offset:6144
	s_waitcnt lgkmcnt(3)
	v_mfma_f32_16x16x32_bf16 v[0:3], v[144:147], v[206:209], v[0:3]
	v_mfma_f32_16x16x32_bf16 v[4:7], v[144:147], v[222:225], v[4:7]
	v_mfma_f32_16x16x32_bf16 v[8:11], v[144:147], v[226:229], v[8:11]
	v_mfma_f32_16x16x32_bf16 v[12:15], v[144:147], v[230:233], v[12:15]
	ds_read_b128 v[144:147], v137 offset:8192
	s_waitcnt lgkmcnt(3)
	v_mfma_f32_16x16x32_bf16 v[16:19], v[148:151], v[206:209], v[16:19]
	v_mfma_f32_16x16x32_bf16 v[20:23], v[148:151], v[222:225], v[20:23]
	v_mfma_f32_16x16x32_bf16 v[24:27], v[148:151], v[226:229], v[24:27]
	v_mfma_f32_16x16x32_bf16 v[28:31], v[148:151], v[230:233], v[28:31]
	ds_read_b128 v[148:151], v137 offset:10240
	s_waitcnt lgkmcnt(3)
	v_mfma_f32_16x16x32_bf16 v[32:35], v[156:159], v[206:209], v[32:35]
	v_mfma_f32_16x16x32_bf16 v[36:39], v[156:159], v[222:225], v[36:39]
	v_mfma_f32_16x16x32_bf16 v[40:43], v[156:159], v[226:229], v[40:43]
	v_mfma_f32_16x16x32_bf16 v[44:47], v[156:159], v[230:233], v[44:47]
	ds_read_b128 v[156:159], v137 offset:12288
	s_waitcnt lgkmcnt(3)
	v_mfma_f32_16x16x32_bf16 v[48:51], v[182:185], v[206:209], v[48:51]
	v_mfma_f32_16x16x32_bf16 v[52:55], v[182:185], v[222:225], v[52:55]
	v_mfma_f32_16x16x32_bf16 v[56:59], v[182:185], v[226:229], v[56:59]
	v_mfma_f32_16x16x32_bf16 v[60:63], v[182:185], v[230:233], v[60:63]
	ds_read_b128 v[182:185], v137 offset:14336
	s_waitcnt lgkmcnt(3)
	v_mfma_f32_16x16x32_bf16 v[64:67], v[144:147], v[206:209], v[64:67]
	v_mfma_f32_16x16x32_bf16 v[68:71], v[144:147], v[222:225], v[68:71]
	v_mfma_f32_16x16x32_bf16 v[72:75], v[144:147], v[226:229], v[72:75]
	v_mfma_f32_16x16x32_bf16 v[76:79], v[144:147], v[230:233], v[76:79]
	s_waitcnt lgkmcnt(2)
	v_mfma_f32_16x16x32_bf16 v[80:83], v[148:151], v[206:209], v[80:83]
	v_mfma_f32_16x16x32_bf16 v[84:87], v[148:151], v[222:225], v[84:87]
	v_mfma_f32_16x16x32_bf16 v[88:91], v[148:151], v[226:229], v[88:91]
	v_mfma_f32_16x16x32_bf16 v[92:95], v[148:151], v[230:233], v[92:95]
	s_waitcnt lgkmcnt(1)
	v_mfma_f32_16x16x32_bf16 v[96:99], v[156:159], v[206:209], v[96:99]
	v_mfma_f32_16x16x32_bf16 v[100:103], v[156:159], v[222:225], v[100:103]
	v_mfma_f32_16x16x32_bf16 v[104:107], v[156:159], v[226:229], v[104:107]
	v_mfma_f32_16x16x32_bf16 v[108:111], v[156:159], v[230:233], v[108:111]
	s_waitcnt lgkmcnt(0)
	v_mfma_f32_16x16x32_bf16 v[112:115], v[182:185], v[206:209], v[112:115]
	v_mfma_f32_16x16x32_bf16 v[116:119], v[182:185], v[222:225], v[116:119]
	v_mfma_f32_16x16x32_bf16 v[120:123], v[182:185], v[226:229], v[120:123]
	v_mfma_f32_16x16x32_bf16 v[124:127], v[182:185], v[230:233], v[124:127]
	s_setprio 0
	v_xor_b32_e32 v136, 0x8000, v136
	v_xor_b32_e32 v137, 0x8000, v137
	s_xor_b32 s25, s25, 0x8000
	s_add_i32 s24, s24, 1
	s_cmp_eq_u32 s24, 16
	s_cbranch_scc0 .Lg_ph11b_top
	s_waitcnt vmcnt(0)
	v_mov_b32_e32 v130, v180
	v_add_u32_e32 v192, 0x400, v166
	v_add_u32_e32 v191, 0x1000, v166
	v_add_u32_e32 v190, 0x1400, v166
	v_add_u32_e32 v189, 0x2000, v166
	v_add_u32_e32 v182, 0x2400, v166
	v_add_u32_e32 v183, 0x3000, v166
	v_add_u32_e32 v184, 0x3200, v166
	v_add_u32_e32 v185, 0x3400, v166
	v_add_u32_e32 v186, 0x3600, v166
	v_add_u32_e32 v187, 0x4000, v166
	v_add_u32_e32 v159, 0x4400, v166
	v_add_u32_e32 v179, 0x4800, v166
	v_add_u32_e32 v181, 0x5000, v166
	v_add_u32_e32 v156, 0x5400, v166
	v_add_u32_e32 v157, 0x5800, v166
	v_add_u32_e32 v158, 0x6000, v166
	v_add_u32_e32 v150, 0x6400, v166
	v_add_u32_e32 v151, 0x6800, v166
	v_add_u32_e32 v152, 0x7200, v166
	v_add_u32_e32 v153, 0x7400, v166
	v_add_u32_e32 v154, 0x7600, v166
	v_add_u32_e32 v155, 0x7800, v166
	v_add_u32_e32 v149, 0x8400, v166
	v_add_u32_e32 v148, 0x8800, v166
	v_add_u32_e32 v147, 0x9400, v166
	v_add_u32_e32 v146, 0x9800, v166
	v_add_u32_e32 v145, 0xa400, v166
	v_add_u32_e32 v140, 0xa800, v166
	v_add_u32_e32 v141, 0xb400, v166
	v_add_u32_e32 v142, 0xb600, v166
	v_add_u32_e32 v143, 0xb800, v166
	v_add_u32_e32 v144, 0xba00, v166
	s_waitcnt vmcnt(0)
	s_barrier
	s_and_saveexec_b64 s[24:25], s[6:7]
	s_cbranch_execz .LBB0_1187
	v_and_b32_e32 v254, 63, v180
	v_lshrrev_b32_e32 v253, 4, v254
	v_mul_u32_u24_e32 v253, 0x840, v253
	v_and_b32_e32 v254, 15, v254
	v_lshl_add_u32 v253, v254, 2, v253
	v_and_b32_e32 v254, 64, v180
	v_lshl_add_u32 v253, v254, 2, v253
	ds_write_b32 v253, v0 offset:0
	ds_write_b32 v253, v1 offset:528
	ds_write_b32 v253, v2 offset:1056
	ds_write_b32 v253, v3 offset:1584
	ds_write_b32 v253, v4 offset:64
	ds_write_b32 v253, v5 offset:592
	ds_write_b32 v253, v6 offset:1120
	ds_write_b32 v253, v7 offset:1648
	ds_write_b32 v253, v8 offset:128
	ds_write_b32 v253, v9 offset:656
	ds_write_b32 v253, v10 offset:1184
	ds_write_b32 v253, v11 offset:1712
	ds_write_b32 v253, v12 offset:192
	ds_write_b32 v253, v13 offset:720
	ds_write_b32 v253, v14 offset:1248
	ds_write_b32 v253, v15 offset:1776
	ds_write_b32 v253, v16 offset:8448
	ds_write_b32 v253, v17 offset:8976
	ds_write_b32 v253, v18 offset:9504
	ds_write_b32 v253, v19 offset:10032
	ds_write_b32 v253, v20 offset:8512
	ds_write_b32 v253, v21 offset:9040
	ds_write_b32 v253, v22 offset:9568
	ds_write_b32 v253, v23 offset:10096
	ds_write_b32 v253, v24 offset:8576
	ds_write_b32 v253, v25 offset:9104
	ds_write_b32 v253, v26 offset:9632
	ds_write_b32 v253, v27 offset:10160
	ds_write_b32 v253, v28 offset:8640
	ds_write_b32 v253, v29 offset:9168
	ds_write_b32 v253, v30 offset:9696
	ds_write_b32 v253, v31 offset:10224
	ds_write_b32 v253, v32 offset:16896
	ds_write_b32 v253, v33 offset:17424
	ds_write_b32 v253, v34 offset:17952
	ds_write_b32 v253, v35 offset:18480
	ds_write_b32 v253, v36 offset:16960
	ds_write_b32 v253, v37 offset:17488
	ds_write_b32 v253, v38 offset:18016
	ds_write_b32 v253, v39 offset:18544
	ds_write_b32 v253, v40 offset:17024
	ds_write_b32 v253, v41 offset:17552
	ds_write_b32 v253, v42 offset:18080
	ds_write_b32 v253, v43 offset:18608
	ds_write_b32 v253, v44 offset:17088
	ds_write_b32 v253, v45 offset:17616
	ds_write_b32 v253, v46 offset:18144
	ds_write_b32 v253, v47 offset:18672
	ds_write_b32 v253, v48 offset:25344
	ds_write_b32 v253, v49 offset:25872
	ds_write_b32 v253, v50 offset:26400
	ds_write_b32 v253, v51 offset:26928
	ds_write_b32 v253, v52 offset:25408
	ds_write_b32 v253, v53 offset:25936
	ds_write_b32 v253, v54 offset:26464
	ds_write_b32 v253, v55 offset:26992
	ds_write_b32 v253, v56 offset:25472
	ds_write_b32 v253, v57 offset:26000
	ds_write_b32 v253, v58 offset:26528
	ds_write_b32 v253, v59 offset:27056
	ds_write_b32 v253, v60 offset:25536
	ds_write_b32 v253, v61 offset:26064
	ds_write_b32 v253, v62 offset:26592
	ds_write_b32 v253, v63 offset:27120
	ds_write_b32 v253, v64 offset:33792
	ds_write_b32 v253, v65 offset:34320
	ds_write_b32 v253, v66 offset:34848
	ds_write_b32 v253, v67 offset:35376
	ds_write_b32 v253, v68 offset:33856
	ds_write_b32 v253, v69 offset:34384
	ds_write_b32 v253, v70 offset:34912
	ds_write_b32 v253, v71 offset:35440
	ds_write_b32 v253, v72 offset:33920
	ds_write_b32 v253, v73 offset:34448
	ds_write_b32 v253, v74 offset:34976
	ds_write_b32 v253, v75 offset:35504
	ds_write_b32 v253, v76 offset:33984
	ds_write_b32 v253, v77 offset:34512
	ds_write_b32 v253, v78 offset:35040
	ds_write_b32 v253, v79 offset:35568
	ds_write_b32 v253, v80 offset:42240
	ds_write_b32 v253, v81 offset:42768
	ds_write_b32 v253, v82 offset:43296
	ds_write_b32 v253, v83 offset:43824
	ds_write_b32 v253, v84 offset:42304
	ds_write_b32 v253, v85 offset:42832
	ds_write_b32 v253, v86 offset:43360
	ds_write_b32 v253, v87 offset:43888
	ds_write_b32 v253, v88 offset:42368
	ds_write_b32 v253, v89 offset:42896
	ds_write_b32 v253, v90 offset:43424
	ds_write_b32 v253, v91 offset:43952
	ds_write_b32 v253, v92 offset:42432
	ds_write_b32 v253, v93 offset:42960
	ds_write_b32 v253, v94 offset:43488
	ds_write_b32 v253, v95 offset:44016
	ds_write_b32 v253, v96 offset:50688
	ds_write_b32 v253, v97 offset:51216
	ds_write_b32 v253, v98 offset:51744
	ds_write_b32 v253, v99 offset:52272
	ds_write_b32 v253, v100 offset:50752
	ds_write_b32 v253, v101 offset:51280
	ds_write_b32 v253, v102 offset:51808
	ds_write_b32 v253, v103 offset:52336
	ds_write_b32 v253, v104 offset:50816
	ds_write_b32 v253, v105 offset:51344
	ds_write_b32 v253, v106 offset:51872
	ds_write_b32 v253, v107 offset:52400
	ds_write_b32 v253, v108 offset:50880
	ds_write_b32 v253, v109 offset:51408
	ds_write_b32 v253, v110 offset:51936
	ds_write_b32 v253, v111 offset:52464
	ds_write_b32 v253, v112 offset:59136
	ds_write_b32 v253, v113 offset:59664
	ds_write_b32 v253, v114 offset:60192
	ds_write_b32 v253, v115 offset:60720
	ds_write_b32 v253, v116 offset:59200
	ds_write_b32 v253, v117 offset:59728
	ds_write_b32 v253, v118 offset:60256
	ds_write_b32 v253, v119 offset:60784
	ds_write_b32 v253, v120 offset:59264
	ds_write_b32 v253, v121 offset:59792
	ds_write_b32 v253, v122 offset:60320
	ds_write_b32 v253, v123 offset:60848
	ds_write_b32 v253, v124 offset:59328
	ds_write_b32 v253, v125 offset:59856
	ds_write_b32 v253, v126 offset:60384
	ds_write_b32 v253, v127 offset:60912

.Lg_ph13_noB:
	s_setprio 1
	s_waitcnt lgkmcnt(3)
	v_mfma_f32_16x16x32_bf16 v[0:3], v[170:173], v[194:197], v[0:3]
	v_mfma_f32_16x16x32_bf16 v[4:7], v[170:173], v[198:201], v[4:7]
	v_mfma_f32_16x16x32_bf16 v[8:11], v[170:173], v[202:205], v[8:11]
	v_mfma_f32_16x16x32_bf16 v[12:15], v[170:173], v[206:209], v[12:15]
	ds_read_b128 v[170:173], v138 offset:8192
	s_waitcnt lgkmcnt(3)
	v_mfma_f32_16x16x32_bf16 v[16:19], v[174:177], v[194:197], v[16:19]
	v_mfma_f32_16x16x32_bf16 v[20:23], v[174:177], v[198:201], v[20:23]
	v_mfma_f32_16x16x32_bf16 v[24:27], v[174:177], v[202:205], v[24:27]
	v_mfma_f32_16x16x32_bf16 v[28:31], v[174:177], v[206:209], v[28:31]
	ds_read_b128 v[174:177], v138 offset:10240
	s_waitcnt lgkmcnt(3)
	v_mfma_f32_16x16x32_bf16 v[32:35], v[182:185], v[194:197], v[32:35]
	v_mfma_f32_16x16x32_bf16 v[36:39], v[182:185], v[198:201], v[36:39]
	v_mfma_f32_16x16x32_bf16 v[40:43], v[182:185], v[202:205], v[40:43]
	v_mfma_f32_16x16x32_bf16 v[44:47], v[182:185], v[206:209], v[44:47]
	ds_read_b128 v[182:185], v138 offset:12288
	s_waitcnt lgkmcnt(3)
	v_mfma_f32_16x16x32_bf16 v[48:51], v[190:193], v[194:197], v[48:51]
	v_mfma_f32_16x16x32_bf16 v[52:55], v[190:193], v[198:201], v[52:55]
	v_mfma_f32_16x16x32_bf16 v[56:59], v[190:193], v[202:205], v[56:59]
	v_mfma_f32_16x16x32_bf16 v[60:63], v[190:193], v[206:209], v[60:63]
	ds_read_b128 v[190:193], v138 offset:14336
	s_waitcnt lgkmcnt(3)
	v_mfma_f32_16x16x32_bf16 v[64:67], v[170:173], v[194:197], v[64:67]
	v_mfma_f32_16x16x32_bf16 v[68:71], v[170:173], v[198:201], v[68:71]
	v_mfma_f32_16x16x32_bf16 v[72:75], v[170:173], v[202:205], v[72:75]
	v_mfma_f32_16x16x32_bf16 v[76:79], v[170:173], v[206:209], v[76:79]
	ds_read_b128 v[170:173], v139
	s_waitcnt lgkmcnt(3)
	v_mfma_f32_16x16x32_bf16 v[80:83], v[174:177], v[194:197], v[80:83]
	v_mfma_f32_16x16x32_bf16 v[84:87], v[174:177], v[198:201], v[84:87]
	v_mfma_f32_16x16x32_bf16 v[88:91], v[174:177], v[202:205], v[88:91]
	v_mfma_f32_16x16x32_bf16 v[92:95], v[174:177], v[206:209], v[92:95]
	ds_read_b128 v[174:177], v139 offset:2048
	s_waitcnt lgkmcnt(3)
	v_mfma_f32_16x16x32_bf16 v[96:99], v[182:185], v[194:197], v[96:99]
	v_mfma_f32_16x16x32_bf16 v[100:103], v[182:185], v[198:201], v[100:103]
	v_mfma_f32_16x16x32_bf16 v[104:107], v[182:185], v[202:205], v[104:107]
	v_mfma_f32_16x16x32_bf16 v[108:111], v[182:185], v[206:209], v[108:111]
	ds_read_b128 v[182:185], v139 offset:4096
	s_waitcnt lgkmcnt(3)
	v_mfma_f32_16x16x32_bf16 v[112:115], v[190:193], v[194:197], v[112:115]
	v_mfma_f32_16x16x32_bf16 v[116:119], v[190:193], v[198:201], v[116:119]
	v_mfma_f32_16x16x32_bf16 v[120:123], v[190:193], v[202:205], v[120:123]
	v_mfma_f32_16x16x32_bf16 v[124:127], v[190:193], v[206:209], v[124:127]
	ds_read_b128 v[190:193], v139 offset:6144
	s_waitcnt lgkmcnt(3)
	v_mfma_f32_16x16x32_bf16 v[0:3], v[170:173], v[214:217], v[0:3]
	v_mfma_f32_16x16x32_bf16 v[4:7], v[170:173], v[222:225], v[4:7]
	v_mfma_f32_16x16x32_bf16 v[8:11], v[170:173], v[226:229], v[8:11]
	v_mfma_f32_16x16x32_bf16 v[12:15], v[170:173], v[230:233], v[12:15]
	ds_read_b128 v[170:173], v139 offset:8192
	s_waitcnt lgkmcnt(3)
	v_mfma_f32_16x16x32_bf16 v[16:19], v[174:177], v[214:217], v[16:19]
	v_mfma_f32_16x16x32_bf16 v[20:23], v[174:177], v[222:225], v[20:23]
	v_mfma_f32_16x16x32_bf16 v[24:27], v[174:177], v[226:229], v[24:27]
	v_mfma_f32_16x16x32_bf16 v[28:31], v[174:177], v[230:233], v[28:31]
	ds_read_b128 v[174:177], v139 offset:10240
	s_waitcnt lgkmcnt(3)
	v_mfma_f32_16x16x32_bf16 v[32:35], v[182:185], v[214:217], v[32:35]
	v_mfma_f32_16x16x32_bf16 v[36:39], v[182:185], v[222:225], v[36:39]
	v_mfma_f32_16x16x32_bf16 v[40:43], v[182:185], v[226:229], v[40:43]
	v_mfma_f32_16x16x32_bf16 v[44:47], v[182:185], v[230:233], v[44:47]
	ds_read_b128 v[182:185], v139 offset:12288
	s_waitcnt lgkmcnt(3)
	v_mfma_f32_16x16x32_bf16 v[48:51], v[190:193], v[214:217], v[48:51]
	v_mfma_f32_16x16x32_bf16 v[52:55], v[190:193], v[222:225], v[52:55]
	v_mfma_f32_16x16x32_bf16 v[56:59], v[190:193], v[226:229], v[56:59]
	v_mfma_f32_16x16x32_bf16 v[60:63], v[190:193], v[230:233], v[60:63]
	ds_read_b128 v[190:193], v139 offset:14336
	s_waitcnt lgkmcnt(3)
	v_mfma_f32_16x16x32_bf16 v[64:67], v[170:173], v[214:217], v[64:67]
	v_mfma_f32_16x16x32_bf16 v[68:71], v[170:173], v[222:225], v[68:71]
	v_mfma_f32_16x16x32_bf16 v[72:75], v[170:173], v[226:229], v[72:75]
	v_mfma_f32_16x16x32_bf16 v[76:79], v[170:173], v[230:233], v[76:79]
	s_waitcnt lgkmcnt(2)
	v_mfma_f32_16x16x32_bf16 v[80:83], v[174:177], v[214:217], v[80:83]
	v_mfma_f32_16x16x32_bf16 v[84:87], v[174:177], v[222:225], v[84:87]
	v_mfma_f32_16x16x32_bf16 v[88:91], v[174:177], v[226:229], v[88:91]
	v_mfma_f32_16x16x32_bf16 v[92:95], v[174:177], v[230:233], v[92:95]
	s_waitcnt lgkmcnt(1)
	v_mfma_f32_16x16x32_bf16 v[96:99], v[182:185], v[214:217], v[96:99]
	v_mfma_f32_16x16x32_bf16 v[100:103], v[182:185], v[222:225], v[100:103]
	v_mfma_f32_16x16x32_bf16 v[104:107], v[182:185], v[226:229], v[104:107]
	v_mfma_f32_16x16x32_bf16 v[108:111], v[182:185], v[230:233], v[108:111]
	s_waitcnt lgkmcnt(0)
	v_mfma_f32_16x16x32_bf16 v[112:115], v[190:193], v[214:217], v[112:115]
	v_mfma_f32_16x16x32_bf16 v[116:119], v[190:193], v[222:225], v[116:119]
	v_mfma_f32_16x16x32_bf16 v[120:123], v[190:193], v[226:229], v[120:123]
	v_mfma_f32_16x16x32_bf16 v[124:127], v[190:193], v[230:233], v[124:127]
	s_setprio 0
	v_xor_b32_e32 v138, 0x8000, v138
	v_xor_b32_e32 v139, 0x8000, v139
	s_xor_b32 s17, s17, 0x8000
	s_add_i32 s16, s16, 1
	s_cmp_eq_u32 s16, 16
	s_cbranch_scc0 .Lg_ph13_top
	s_waitcnt vmcnt(0)
	v_mov_b32_e32 v130, v180
	v_add_u32_e32 v202, 0x400, v153
	v_add_u32_e32 v201, 0x1000, v153
	v_add_u32_e32 v200, 0x1400, v153
	v_add_u32_e32 v199, 0x2000, v153
	v_add_u32_e32 v193, 0x2400, v153
	v_add_u32_e32 v194, 0x3000, v153
	v_add_u32_e32 v195, 0x3200, v153
	v_add_u32_e32 v196, 0x3400, v153
	v_add_u32_e32 v197, 0x3600, v153
	v_add_u32_e32 v198, 0x4000, v153
	v_add_u32_e32 v190, 0x4400, v153
	v_add_u32_e32 v191, 0x4800, v153
	v_add_u32_e32 v192, 0x5000, v153
	v_add_u32_e32 v186, 0x5400, v153
	v_add_u32_e32 v187, 0x5800, v153
	v_add_u32_e32 v189, 0x6000, v153
	v_add_u32_e32 v179, 0x6400, v153
	v_add_u32_e32 v181, 0x6800, v153
	v_add_u32_e32 v182, 0x7200, v153
	v_add_u32_e32 v183, 0x7400, v153
	v_add_u32_e32 v184, 0x7600, v153
	v_add_u32_e32 v185, 0x7800, v153
	v_add_u32_e32 v178, 0x8400, v153
	v_add_u32_e32 v177, 0x8800, v153
	v_add_u32_e32 v176, 0x9400, v153
	v_add_u32_e32 v175, 0x9800, v153
	v_add_u32_e32 v174, 0xa400, v153
	v_add_u32_e32 v147, 0xa800, v153
	v_add_u32_e32 v169, 0xb400, v153
	v_add_u32_e32 v170, 0xb600, v153
	v_add_u32_e32 v171, 0xb800, v153
	v_add_u32_e32 v172, 0xba00, v153
	s_waitcnt vmcnt(0)
	s_barrier
	s_and_saveexec_b64 s[16:17], s[6:7]
	s_cbranch_execz .LBB0_1319
	v_and_b32_e32 v254, 63, v180
	v_lshrrev_b32_e32 v253, 4, v254
	v_mul_u32_u24_e32 v253, 0x840, v253
	v_and_b32_e32 v254, 15, v254
	v_lshl_add_u32 v253, v254, 2, v253
	v_and_b32_e32 v254, 64, v180
	v_lshl_add_u32 v253, v254, 2, v253
	ds_write_b32 v253, v0 offset:0
	ds_write_b32 v253, v1 offset:528
	ds_write_b32 v253, v2 offset:1056
	ds_write_b32 v253, v3 offset:1584
	ds_write_b32 v253, v4 offset:64
	ds_write_b32 v253, v5 offset:592
	ds_write_b32 v253, v6 offset:1120
	ds_write_b32 v253, v7 offset:1648
	ds_write_b32 v253, v8 offset:128
	ds_write_b32 v253, v9 offset:656
	ds_write_b32 v253, v10 offset:1184
	ds_write_b32 v253, v11 offset:1712
	ds_write_b32 v253, v12 offset:192
	ds_write_b32 v253, v13 offset:720
	ds_write_b32 v253, v14 offset:1248
	ds_write_b32 v253, v15 offset:1776
	ds_write_b32 v253, v16 offset:8448
	ds_write_b32 v253, v17 offset:8976
	ds_write_b32 v253, v18 offset:9504
	ds_write_b32 v253, v19 offset:10032
	ds_write_b32 v253, v20 offset:8512
	ds_write_b32 v253, v21 offset:9040
	ds_write_b32 v253, v22 offset:9568
	ds_write_b32 v253, v23 offset:10096
	ds_write_b32 v253, v24 offset:8576
	ds_write_b32 v253, v25 offset:9104
	ds_write_b32 v253, v26 offset:9632
	ds_write_b32 v253, v27 offset:10160
	ds_write_b32 v253, v28 offset:8640
	ds_write_b32 v253, v29 offset:9168
	ds_write_b32 v253, v30 offset:9696
	ds_write_b32 v253, v31 offset:10224
	ds_write_b32 v253, v32 offset:16896
	ds_write_b32 v253, v33 offset:17424
	ds_write_b32 v253, v34 offset:17952
	ds_write_b32 v253, v35 offset:18480
	ds_write_b32 v253, v36 offset:16960
	ds_write_b32 v253, v37 offset:17488
	ds_write_b32 v253, v38 offset:18016
	ds_write_b32 v253, v39 offset:18544
	ds_write_b32 v253, v40 offset:17024
	ds_write_b32 v253, v41 offset:17552
	ds_write_b32 v253, v42 offset:18080
	ds_write_b32 v253, v43 offset:18608
	ds_write_b32 v253, v44 offset:17088
	ds_write_b32 v253, v45 offset:17616
	ds_write_b32 v253, v46 offset:18144
	ds_write_b32 v253, v47 offset:18672
	ds_write_b32 v253, v48 offset:25344
	ds_write_b32 v253, v49 offset:25872
	ds_write_b32 v253, v50 offset:26400
	ds_write_b32 v253, v51 offset:26928
	ds_write_b32 v253, v52 offset:25408
	ds_write_b32 v253, v53 offset:25936
	ds_write_b32 v253, v54 offset:26464
	ds_write_b32 v253, v55 offset:26992
	ds_write_b32 v253, v56 offset:25472
	ds_write_b32 v253, v57 offset:26000
	ds_write_b32 v253, v58 offset:26528
	ds_write_b32 v253, v59 offset:27056
	ds_write_b32 v253, v60 offset:25536
	ds_write_b32 v253, v61 offset:26064
	ds_write_b32 v253, v62 offset:26592
	ds_write_b32 v253, v63 offset:27120
	ds_write_b32 v253, v64 offset:33792
	ds_write_b32 v253, v65 offset:34320
	ds_write_b32 v253, v66 offset:34848
	ds_write_b32 v253, v67 offset:35376
	ds_write_b32 v253, v68 offset:33856
	ds_write_b32 v253, v69 offset:34384
	ds_write_b32 v253, v70 offset:34912
	ds_write_b32 v253, v71 offset:35440
	ds_write_b32 v253, v72 offset:33920
	ds_write_b32 v253, v73 offset:34448
	ds_write_b32 v253, v74 offset:34976
	ds_write_b32 v253, v75 offset:35504
	ds_write_b32 v253, v76 offset:33984
	ds_write_b32 v253, v77 offset:34512
	ds_write_b32 v253, v78 offset:35040
	ds_write_b32 v253, v79 offset:35568
	ds_write_b32 v253, v80 offset:42240
	ds_write_b32 v253, v81 offset:42768
	ds_write_b32 v253, v82 offset:43296
	ds_write_b32 v253, v83 offset:43824
	ds_write_b32 v253, v84 offset:42304
	ds_write_b32 v253, v85 offset:42832
	ds_write_b32 v253, v86 offset:43360
	ds_write_b32 v253, v87 offset:43888
	ds_write_b32 v253, v88 offset:42368
	ds_write_b32 v253, v89 offset:42896
	ds_write_b32 v253, v90 offset:43424
	ds_write_b32 v253, v91 offset:43952
	ds_write_b32 v253, v92 offset:42432
	ds_write_b32 v253, v93 offset:42960
	ds_write_b32 v253, v94 offset:43488
	ds_write_b32 v253, v95 offset:44016
	ds_write_b32 v253, v96 offset:50688
	ds_write_b32 v253, v97 offset:51216
	ds_write_b32 v253, v98 offset:51744
	ds_write_b32 v253, v99 offset:52272
	ds_write_b32 v253, v100 offset:50752
	ds_write_b32 v253, v101 offset:51280
	ds_write_b32 v253, v102 offset:51808
	ds_write_b32 v253, v103 offset:52336
	ds_write_b32 v253, v104 offset:50816
	ds_write_b32 v253, v105 offset:51344
	ds_write_b32 v253, v106 offset:51872
	ds_write_b32 v253, v107 offset:52400
	ds_write_b32 v253, v108 offset:50880
	ds_write_b32 v253, v109 offset:51408
	ds_write_b32 v253, v110 offset:51936
	ds_write_b32 v253, v111 offset:52464
	ds_write_b32 v253, v112 offset:59136
	ds_write_b32 v253, v113 offset:59664
	ds_write_b32 v253, v114 offset:60192
	ds_write_b32 v253, v115 offset:60720
	ds_write_b32 v253, v116 offset:59200
	ds_write_b32 v253, v117 offset:59728
	ds_write_b32 v253, v118 offset:60256
	ds_write_b32 v253, v119 offset:60784
	ds_write_b32 v253, v120 offset:59264
	ds_write_b32 v253, v121 offset:59792
	ds_write_b32 v253, v122 offset:60320
	ds_write_b32 v253, v123 offset:60848
	ds_write_b32 v253, v124 offset:59328
	ds_write_b32 v253, v125 offset:59856
	ds_write_b32 v253, v126 offset:60384
	ds_write_b32 v253, v127 offset:60912

.Lg_ph16_noB:
	s_setprio 1
	s_waitcnt lgkmcnt(3)
	v_mfma_f32_16x16x32_bf16 v[0:3], v[166:169], v[186:189], v[0:3]
	v_mfma_f32_16x16x32_bf16 v[4:7], v[166:169], v[190:193], v[4:7]
	v_mfma_f32_16x16x32_bf16 v[8:11], v[166:169], v[194:197], v[8:11]
	v_mfma_f32_16x16x32_bf16 v[12:15], v[166:169], v[198:201], v[12:15]
	ds_read_b128 v[166:169], v138 offset:8192
	s_waitcnt lgkmcnt(3)
	v_mfma_f32_16x16x32_bf16 v[16:19], v[170:173], v[186:189], v[16:19]
	v_mfma_f32_16x16x32_bf16 v[20:23], v[170:173], v[190:193], v[20:23]
	v_mfma_f32_16x16x32_bf16 v[24:27], v[170:173], v[194:197], v[24:27]
	v_mfma_f32_16x16x32_bf16 v[28:31], v[170:173], v[198:201], v[28:31]
	ds_read_b128 v[170:173], v138 offset:10240
	s_waitcnt lgkmcnt(3)
	v_mfma_f32_16x16x32_bf16 v[32:35], v[174:177], v[186:189], v[32:35]
	v_mfma_f32_16x16x32_bf16 v[36:39], v[174:177], v[190:193], v[36:39]
	v_mfma_f32_16x16x32_bf16 v[40:43], v[174:177], v[194:197], v[40:43]
	v_mfma_f32_16x16x32_bf16 v[44:47], v[174:177], v[198:201], v[44:47]
	ds_read_b128 v[174:177], v138 offset:12288
	s_waitcnt lgkmcnt(3)
	v_mfma_f32_16x16x32_bf16 v[48:51], v[182:185], v[186:189], v[48:51]
	v_mfma_f32_16x16x32_bf16 v[52:55], v[182:185], v[190:193], v[52:55]
	v_mfma_f32_16x16x32_bf16 v[56:59], v[182:185], v[194:197], v[56:59]
	v_mfma_f32_16x16x32_bf16 v[60:63], v[182:185], v[198:201], v[60:63]
	ds_read_b128 v[182:185], v138 offset:14336
	s_waitcnt lgkmcnt(3)
	v_mfma_f32_16x16x32_bf16 v[64:67], v[166:169], v[186:189], v[64:67]
	v_mfma_f32_16x16x32_bf16 v[68:71], v[166:169], v[190:193], v[68:71]
	v_mfma_f32_16x16x32_bf16 v[72:75], v[166:169], v[194:197], v[72:75]
	v_mfma_f32_16x16x32_bf16 v[76:79], v[166:169], v[198:201], v[76:79]
	ds_read_b128 v[166:169], v139
	s_waitcnt lgkmcnt(3)
	v_mfma_f32_16x16x32_bf16 v[80:83], v[170:173], v[186:189], v[80:83]
	v_mfma_f32_16x16x32_bf16 v[84:87], v[170:173], v[190:193], v[84:87]
	v_mfma_f32_16x16x32_bf16 v[88:91], v[170:173], v[194:197], v[88:91]
	v_mfma_f32_16x16x32_bf16 v[92:95], v[170:173], v[198:201], v[92:95]
	ds_read_b128 v[170:173], v139 offset:2048
	s_waitcnt lgkmcnt(3)
	v_mfma_f32_16x16x32_bf16 v[96:99], v[174:177], v[186:189], v[96:99]
	v_mfma_f32_16x16x32_bf16 v[100:103], v[174:177], v[190:193], v[100:103]
	v_mfma_f32_16x16x32_bf16 v[104:107], v[174:177], v[194:197], v[104:107]
	v_mfma_f32_16x16x32_bf16 v[108:111], v[174:177], v[198:201], v[108:111]
	ds_read_b128 v[174:177], v139 offset:4096
	s_waitcnt lgkmcnt(3)
	v_mfma_f32_16x16x32_bf16 v[112:115], v[182:185], v[186:189], v[112:115]
	v_mfma_f32_16x16x32_bf16 v[116:119], v[182:185], v[190:193], v[116:119]
	v_mfma_f32_16x16x32_bf16 v[120:123], v[182:185], v[194:197], v[120:123]
	v_mfma_f32_16x16x32_bf16 v[124:127], v[182:185], v[198:201], v[124:127]
	ds_read_b128 v[182:185], v139 offset:6144
	s_waitcnt lgkmcnt(3)
	v_mfma_f32_16x16x32_bf16 v[0:3], v[166:169], v[202:205], v[0:3]
	v_mfma_f32_16x16x32_bf16 v[4:7], v[166:169], v[218:221], v[4:7]
	v_mfma_f32_16x16x32_bf16 v[8:11], v[166:169], v[222:225], v[8:11]
	v_mfma_f32_16x16x32_bf16 v[12:15], v[166:169], v[226:229], v[12:15]
	ds_read_b128 v[166:169], v139 offset:8192
	s_waitcnt lgkmcnt(3)
	v_mfma_f32_16x16x32_bf16 v[16:19], v[170:173], v[202:205], v[16:19]
	v_mfma_f32_16x16x32_bf16 v[20:23], v[170:173], v[218:221], v[20:23]
	v_mfma_f32_16x16x32_bf16 v[24:27], v[170:173], v[222:225], v[24:27]
	v_mfma_f32_16x16x32_bf16 v[28:31], v[170:173], v[226:229], v[28:31]
	ds_read_b128 v[170:173], v139 offset:10240
	s_waitcnt lgkmcnt(3)
	v_mfma_f32_16x16x32_bf16 v[32:35], v[174:177], v[202:205], v[32:35]
	v_mfma_f32_16x16x32_bf16 v[36:39], v[174:177], v[218:221], v[36:39]
	v_mfma_f32_16x16x32_bf16 v[40:43], v[174:177], v[222:225], v[40:43]
	v_mfma_f32_16x16x32_bf16 v[44:47], v[174:177], v[226:229], v[44:47]
	ds_read_b128 v[174:177], v139 offset:12288
	s_waitcnt lgkmcnt(3)
	v_mfma_f32_16x16x32_bf16 v[48:51], v[182:185], v[202:205], v[48:51]
	v_mfma_f32_16x16x32_bf16 v[52:55], v[182:185], v[218:221], v[52:55]
	v_mfma_f32_16x16x32_bf16 v[56:59], v[182:185], v[222:225], v[56:59]
	v_mfma_f32_16x16x32_bf16 v[60:63], v[182:185], v[226:229], v[60:63]
	ds_read_b128 v[182:185], v139 offset:14336
	s_waitcnt lgkmcnt(3)
	v_mfma_f32_16x16x32_bf16 v[64:67], v[166:169], v[202:205], v[64:67]
	v_mfma_f32_16x16x32_bf16 v[68:71], v[166:169], v[218:221], v[68:71]
	v_mfma_f32_16x16x32_bf16 v[72:75], v[166:169], v[222:225], v[72:75]
	v_mfma_f32_16x16x32_bf16 v[76:79], v[166:169], v[226:229], v[76:79]
	s_waitcnt lgkmcnt(2)
	v_mfma_f32_16x16x32_bf16 v[80:83], v[170:173], v[202:205], v[80:83]
	v_mfma_f32_16x16x32_bf16 v[84:87], v[170:173], v[218:221], v[84:87]
	v_mfma_f32_16x16x32_bf16 v[88:91], v[170:173], v[222:225], v[88:91]
	v_mfma_f32_16x16x32_bf16 v[92:95], v[170:173], v[226:229], v[92:95]
	s_waitcnt lgkmcnt(1)
	v_mfma_f32_16x16x32_bf16 v[96:99], v[174:177], v[202:205], v[96:99]
	v_mfma_f32_16x16x32_bf16 v[100:103], v[174:177], v[218:221], v[100:103]
	v_mfma_f32_16x16x32_bf16 v[104:107], v[174:177], v[222:225], v[104:107]
	v_mfma_f32_16x16x32_bf16 v[108:111], v[174:177], v[226:229], v[108:111]
	s_waitcnt lgkmcnt(0)
	v_mfma_f32_16x16x32_bf16 v[112:115], v[182:185], v[202:205], v[112:115]
	v_mfma_f32_16x16x32_bf16 v[116:119], v[182:185], v[218:221], v[116:119]
	v_mfma_f32_16x16x32_bf16 v[120:123], v[182:185], v[222:225], v[120:123]
	v_mfma_f32_16x16x32_bf16 v[124:127], v[182:185], v[226:229], v[124:127]
	s_setprio 0
	v_xor_b32_e32 v138, 0x8000, v138
	v_xor_b32_e32 v139, 0x8000, v139
	s_xor_b32 s15, s15, 0x8000
	s_add_i32 s14, s14, 1
	s_cmp_eq_u32 s14, 16
	s_cbranch_scc0 .Lg_ph16_top
	s_waitcnt vmcnt(0)
	v_mov_b32_e32 v128, v180
	v_add_u32_e32 v192, 0x400, v153
	v_add_u32_e32 v191, 0x1000, v153
	v_add_u32_e32 v190, 0x1400, v153
	v_add_u32_e32 v189, 0x2000, v153
	v_add_u32_e32 v183, 0x2400, v153
	v_add_u32_e32 v184, 0x3000, v153
	v_add_u32_e32 v185, 0x3200, v153
	v_add_u32_e32 v186, 0x3400, v153
	v_add_u32_e32 v187, 0x3600, v153
	v_add_u32_e32 v188, 0x4000, v153
	v_add_u32_e32 v179, 0x4400, v153
	v_add_u32_e32 v181, 0x4800, v153
	v_add_u32_e32 v182, 0x5000, v153
	v_add_u32_e32 v176, 0x5400, v153
	v_add_u32_e32 v177, 0x5800, v153
	v_add_u32_e32 v178, 0x6000, v153
	v_add_u32_e32 v170, 0x6400, v153
	v_add_u32_e32 v171, 0x6800, v153
	v_add_u32_e32 v172, 0x7200, v153
	v_add_u32_e32 v173, 0x7400, v153
	v_add_u32_e32 v174, 0x7600, v153
	v_add_u32_e32 v175, 0x7800, v153
	v_add_u32_e32 v169, 0x8400, v153
	v_add_u32_e32 v168, 0x8800, v153
	v_add_u32_e32 v167, 0x9400, v153
	v_add_u32_e32 v166, 0x9800, v153
	v_add_u32_e32 v145, 0xa400, v153
	v_add_u32_e32 v140, 0xa800, v153
	v_add_u32_e32 v141, 0xb400, v153
	v_add_u32_e32 v142, 0xb600, v153
	v_add_u32_e32 v143, 0xb800, v153
	v_add_u32_e32 v144, 0xba00, v153
	s_waitcnt vmcnt(0)
	s_barrier
	s_and_saveexec_b64 s[14:15], s[6:7]
	s_cbranch_execz .LBB0_1674
	v_and_b32_e32 v254, 63, v180
	v_lshrrev_b32_e32 v253, 4, v254
	v_mul_u32_u24_e32 v253, 0x840, v253
	v_and_b32_e32 v254, 15, v254
	v_lshl_add_u32 v253, v254, 2, v253
	v_and_b32_e32 v254, 64, v180
	v_lshl_add_u32 v253, v254, 2, v253
	ds_write_b32 v253, v0 offset:0
	ds_write_b32 v253, v1 offset:528
	ds_write_b32 v253, v2 offset:1056
	ds_write_b32 v253, v3 offset:1584
	ds_write_b32 v253, v4 offset:64
	ds_write_b32 v253, v5 offset:592
	ds_write_b32 v253, v6 offset:1120
	ds_write_b32 v253, v7 offset:1648
	ds_write_b32 v253, v8 offset:128
	ds_write_b32 v253, v9 offset:656
	ds_write_b32 v253, v10 offset:1184
	ds_write_b32 v253, v11 offset:1712
	ds_write_b32 v253, v12 offset:192
	ds_write_b32 v253, v13 offset:720
	ds_write_b32 v253, v14 offset:1248
	ds_write_b32 v253, v15 offset:1776
	ds_write_b32 v253, v16 offset:8448
	ds_write_b32 v253, v17 offset:8976
	ds_write_b32 v253, v18 offset:9504
	ds_write_b32 v253, v19 offset:10032
	ds_write_b32 v253, v20 offset:8512
	ds_write_b32 v253, v21 offset:9040
	ds_write_b32 v253, v22 offset:9568
	ds_write_b32 v253, v23 offset:10096
	ds_write_b32 v253, v24 offset:8576
	ds_write_b32 v253, v25 offset:9104
	ds_write_b32 v253, v26 offset:9632
	ds_write_b32 v253, v27 offset:10160
	ds_write_b32 v253, v28 offset:8640
	ds_write_b32 v253, v29 offset:9168
	ds_write_b32 v253, v30 offset:9696
	ds_write_b32 v253, v31 offset:10224
	ds_write_b32 v253, v32 offset:16896
	ds_write_b32 v253, v33 offset:17424
	ds_write_b32 v253, v34 offset:17952
	ds_write_b32 v253, v35 offset:18480
	ds_write_b32 v253, v36 offset:16960
	ds_write_b32 v253, v37 offset:17488
	ds_write_b32 v253, v38 offset:18016
	ds_write_b32 v253, v39 offset:18544
	ds_write_b32 v253, v40 offset:17024
	ds_write_b32 v253, v41 offset:17552
	ds_write_b32 v253, v42 offset:18080
	ds_write_b32 v253, v43 offset:18608
	ds_write_b32 v253, v44 offset:17088
	ds_write_b32 v253, v45 offset:17616
	ds_write_b32 v253, v46 offset:18144
	ds_write_b32 v253, v47 offset:18672
	ds_write_b32 v253, v48 offset:25344
	ds_write_b32 v253, v49 offset:25872
	ds_write_b32 v253, v50 offset:26400
	ds_write_b32 v253, v51 offset:26928
	ds_write_b32 v253, v52 offset:25408
	ds_write_b32 v253, v53 offset:25936
	ds_write_b32 v253, v54 offset:26464
	ds_write_b32 v253, v55 offset:26992
	ds_write_b32 v253, v56 offset:25472
	ds_write_b32 v253, v57 offset:26000
	ds_write_b32 v253, v58 offset:26528
	ds_write_b32 v253, v59 offset:27056
	ds_write_b32 v253, v60 offset:25536
	ds_write_b32 v253, v61 offset:26064
	ds_write_b32 v253, v62 offset:26592
	ds_write_b32 v253, v63 offset:27120
	ds_write_b32 v253, v64 offset:33792
	ds_write_b32 v253, v65 offset:34320
	ds_write_b32 v253, v66 offset:34848
	ds_write_b32 v253, v67 offset:35376
	ds_write_b32 v253, v68 offset:33856
	ds_write_b32 v253, v69 offset:34384
	ds_write_b32 v253, v70 offset:34912
	ds_write_b32 v253, v71 offset:35440
	ds_write_b32 v253, v72 offset:33920
	ds_write_b32 v253, v73 offset:34448
	ds_write_b32 v253, v74 offset:34976
	ds_write_b32 v253, v75 offset:35504
	ds_write_b32 v253, v76 offset:33984
	ds_write_b32 v253, v77 offset:34512
	ds_write_b32 v253, v78 offset:35040
	ds_write_b32 v253, v79 offset:35568
	ds_write_b32 v253, v80 offset:42240
	ds_write_b32 v253, v81 offset:42768
	ds_write_b32 v253, v82 offset:43296
	ds_write_b32 v253, v83 offset:43824
	ds_write_b32 v253, v84 offset:42304
	ds_write_b32 v253, v85 offset:42832
	ds_write_b32 v253, v86 offset:43360
	ds_write_b32 v253, v87 offset:43888
	ds_write_b32 v253, v88 offset:42368
	ds_write_b32 v253, v89 offset:42896
	ds_write_b32 v253, v90 offset:43424
	ds_write_b32 v253, v91 offset:43952
	ds_write_b32 v253, v92 offset:42432
	ds_write_b32 v253, v93 offset:42960
	ds_write_b32 v253, v94 offset:43488
	ds_write_b32 v253, v95 offset:44016
	ds_write_b32 v253, v96 offset:50688
	ds_write_b32 v253, v97 offset:51216
	ds_write_b32 v253, v98 offset:51744
	ds_write_b32 v253, v99 offset:52272
	ds_write_b32 v253, v100 offset:50752
	ds_write_b32 v253, v101 offset:51280
	ds_write_b32 v253, v102 offset:51808
	ds_write_b32 v253, v103 offset:52336
	ds_write_b32 v253, v104 offset:50816
	ds_write_b32 v253, v105 offset:51344
	ds_write_b32 v253, v106 offset:51872
	ds_write_b32 v253, v107 offset:52400
	ds_write_b32 v253, v108 offset:50880
	ds_write_b32 v253, v109 offset:51408
	ds_write_b32 v253, v110 offset:51936
	ds_write_b32 v253, v111 offset:52464
	ds_write_b32 v253, v112 offset:59136
	ds_write_b32 v253, v113 offset:59664
	ds_write_b32 v253, v114 offset:60192
	ds_write_b32 v253, v115 offset:60720
	ds_write_b32 v253, v116 offset:59200
	ds_write_b32 v253, v117 offset:59728
	ds_write_b32 v253, v118 offset:60256
	ds_write_b32 v253, v119 offset:60784
	ds_write_b32 v253, v120 offset:59264
	ds_write_b32 v253, v121 offset:59792
	ds_write_b32 v253, v122 offset:60320
	ds_write_b32 v253, v123 offset:60848
	ds_write_b32 v253, v124 offset:59328
	ds_write_b32 v253, v125 offset:59856
	ds_write_b32 v253, v126 offset:60384
	ds_write_b32 v253, v127 offset:60912

.Lg_ph17_noB:
	s_setprio 1
	s_waitcnt lgkmcnt(3)
	v_mfma_f32_16x16x32_bf16 v[0:3], v[148:151], v[190:193], v[0:3]
	v_mfma_f32_16x16x32_bf16 v[4:7], v[148:151], v[194:197], v[4:7]
	v_mfma_f32_16x16x32_bf16 v[8:11], v[148:151], v[198:201], v[8:11]
	v_mfma_f32_16x16x32_bf16 v[12:15], v[148:151], v[202:205], v[12:15]
	ds_read_b128 v[148:151], v138 offset:8192
	s_waitcnt lgkmcnt(3)
	v_mfma_f32_16x16x32_bf16 v[16:19], v[174:177], v[190:193], v[16:19]
	v_mfma_f32_16x16x32_bf16 v[20:23], v[174:177], v[194:197], v[20:23]
	v_mfma_f32_16x16x32_bf16 v[24:27], v[174:177], v[198:201], v[24:27]
	v_mfma_f32_16x16x32_bf16 v[28:31], v[174:177], v[202:205], v[28:31]
	ds_read_b128 v[174:177], v138 offset:10240
	s_waitcnt lgkmcnt(3)
	v_mfma_f32_16x16x32_bf16 v[32:35], v[182:185], v[190:193], v[32:35]
	v_mfma_f32_16x16x32_bf16 v[36:39], v[182:185], v[194:197], v[36:39]
	v_mfma_f32_16x16x32_bf16 v[40:43], v[182:185], v[198:201], v[40:43]
	v_mfma_f32_16x16x32_bf16 v[44:47], v[182:185], v[202:205], v[44:47]
	ds_read_b128 v[182:185], v138 offset:12288
	s_waitcnt lgkmcnt(3)
	v_mfma_f32_16x16x32_bf16 v[48:51], v[186:189], v[190:193], v[48:51]
	v_mfma_f32_16x16x32_bf16 v[52:55], v[186:189], v[194:197], v[52:55]
	v_mfma_f32_16x16x32_bf16 v[56:59], v[186:189], v[198:201], v[56:59]
	v_mfma_f32_16x16x32_bf16 v[60:63], v[186:189], v[202:205], v[60:63]
	ds_read_b128 v[186:189], v138 offset:14336
	s_waitcnt lgkmcnt(3)
	v_mfma_f32_16x16x32_bf16 v[64:67], v[148:151], v[190:193], v[64:67]
	v_mfma_f32_16x16x32_bf16 v[68:71], v[148:151], v[194:197], v[68:71]
	v_mfma_f32_16x16x32_bf16 v[72:75], v[148:151], v[198:201], v[72:75]
	v_mfma_f32_16x16x32_bf16 v[76:79], v[148:151], v[202:205], v[76:79]
	ds_read_b128 v[148:151], v139
	s_waitcnt lgkmcnt(3)
	v_mfma_f32_16x16x32_bf16 v[80:83], v[174:177], v[190:193], v[80:83]
	v_mfma_f32_16x16x32_bf16 v[84:87], v[174:177], v[194:197], v[84:87]
	v_mfma_f32_16x16x32_bf16 v[88:91], v[174:177], v[198:201], v[88:91]
	v_mfma_f32_16x16x32_bf16 v[92:95], v[174:177], v[202:205], v[92:95]
	ds_read_b128 v[174:177], v139 offset:2048
	s_waitcnt lgkmcnt(3)
	v_mfma_f32_16x16x32_bf16 v[96:99], v[182:185], v[190:193], v[96:99]
	v_mfma_f32_16x16x32_bf16 v[100:103], v[182:185], v[194:197], v[100:103]
	v_mfma_f32_16x16x32_bf16 v[104:107], v[182:185], v[198:201], v[104:107]
	v_mfma_f32_16x16x32_bf16 v[108:111], v[182:185], v[202:205], v[108:111]
	ds_read_b128 v[182:185], v139 offset:4096
	s_waitcnt lgkmcnt(3)
	v_mfma_f32_16x16x32_bf16 v[112:115], v[186:189], v[190:193], v[112:115]
	v_mfma_f32_16x16x32_bf16 v[116:119], v[186:189], v[194:197], v[116:119]
	v_mfma_f32_16x16x32_bf16 v[120:123], v[186:189], v[198:201], v[120:123]
	v_mfma_f32_16x16x32_bf16 v[124:127], v[186:189], v[202:205], v[124:127]
	ds_read_b128 v[186:189], v139 offset:6144
	s_waitcnt lgkmcnt(3)
	v_mfma_f32_16x16x32_bf16 v[0:3], v[148:151], v[206:209], v[0:3]
	v_mfma_f32_16x16x32_bf16 v[4:7], v[148:151], v[224:227], v[4:7]
	v_mfma_f32_16x16x32_bf16 v[8:11], v[148:151], v[228:231], v[8:11]
	v_mfma_f32_16x16x32_bf16 v[12:15], v[148:151], v[232:235], v[12:15]
	ds_read_b128 v[148:151], v139 offset:8192
	s_waitcnt lgkmcnt(3)
	v_mfma_f32_16x16x32_bf16 v[16:19], v[174:177], v[206:209], v[16:19]
	v_mfma_f32_16x16x32_bf16 v[20:23], v[174:177], v[224:227], v[20:23]
	v_mfma_f32_16x16x32_bf16 v[24:27], v[174:177], v[228:231], v[24:27]
	v_mfma_f32_16x16x32_bf16 v[28:31], v[174:177], v[232:235], v[28:31]
	ds_read_b128 v[174:177], v139 offset:10240
	s_waitcnt lgkmcnt(3)
	v_mfma_f32_16x16x32_bf16 v[32:35], v[182:185], v[206:209], v[32:35]
	v_mfma_f32_16x16x32_bf16 v[36:39], v[182:185], v[224:227], v[36:39]
	v_mfma_f32_16x16x32_bf16 v[40:43], v[182:185], v[228:231], v[40:43]
	v_mfma_f32_16x16x32_bf16 v[44:47], v[182:185], v[232:235], v[44:47]
	ds_read_b128 v[182:185], v139 offset:12288
	s_waitcnt lgkmcnt(3)
	v_mfma_f32_16x16x32_bf16 v[48:51], v[186:189], v[206:209], v[48:51]
	v_mfma_f32_16x16x32_bf16 v[52:55], v[186:189], v[224:227], v[52:55]
	v_mfma_f32_16x16x32_bf16 v[56:59], v[186:189], v[228:231], v[56:59]
	v_mfma_f32_16x16x32_bf16 v[60:63], v[186:189], v[232:235], v[60:63]
	ds_read_b128 v[186:189], v139 offset:14336
	s_waitcnt lgkmcnt(3)
	v_mfma_f32_16x16x32_bf16 v[64:67], v[148:151], v[206:209], v[64:67]
	v_mfma_f32_16x16x32_bf16 v[68:71], v[148:151], v[224:227], v[68:71]
	v_mfma_f32_16x16x32_bf16 v[72:75], v[148:151], v[228:231], v[72:75]
	v_mfma_f32_16x16x32_bf16 v[76:79], v[148:151], v[232:235], v[76:79]
	s_waitcnt lgkmcnt(2)
	v_mfma_f32_16x16x32_bf16 v[80:83], v[174:177], v[206:209], v[80:83]
	v_mfma_f32_16x16x32_bf16 v[84:87], v[174:177], v[224:227], v[84:87]
	v_mfma_f32_16x16x32_bf16 v[88:91], v[174:177], v[228:231], v[88:91]
	v_mfma_f32_16x16x32_bf16 v[92:95], v[174:177], v[232:235], v[92:95]
	s_waitcnt lgkmcnt(1)
	v_mfma_f32_16x16x32_bf16 v[96:99], v[182:185], v[206:209], v[96:99]
	v_mfma_f32_16x16x32_bf16 v[100:103], v[182:185], v[224:227], v[100:103]
	v_mfma_f32_16x16x32_bf16 v[104:107], v[182:185], v[228:231], v[104:107]
	v_mfma_f32_16x16x32_bf16 v[108:111], v[182:185], v[232:235], v[108:111]
	s_waitcnt lgkmcnt(0)
	v_mfma_f32_16x16x32_bf16 v[112:115], v[186:189], v[206:209], v[112:115]
	v_mfma_f32_16x16x32_bf16 v[116:119], v[186:189], v[224:227], v[116:119]
	v_mfma_f32_16x16x32_bf16 v[120:123], v[186:189], v[228:231], v[120:123]
	v_mfma_f32_16x16x32_bf16 v[124:127], v[186:189], v[232:235], v[124:127]
	s_setprio 0
	v_xor_b32_e32 v138, 0x8000, v138
	v_xor_b32_e32 v139, 0x8000, v139
	s_xor_b32 s21, s21, 0x8000
	s_add_i32 s20, s20, 1
	s_cmp_eq_u32 s20, 16
	s_cbranch_scc0 .Lg_ph17_top
	s_waitcnt vmcnt(0)
	v_mov_b32_e32 v146, v180
	v_add_u32_e32 v208, 0x400, v157
	v_add_u32_e32 v207, 0x1000, v157
	v_add_u32_e32 v206, 0x1400, v157
	v_add_u32_e32 v205, 0x2000, v157
	v_add_u32_e32 v199, 0x2400, v157
	v_add_u32_e32 v200, 0x3000, v157
	v_add_u32_e32 v201, 0x3200, v157
	v_add_u32_e32 v202, 0x3400, v157
	v_add_u32_e32 v203, 0x3600, v157
	v_add_u32_e32 v204, 0x4000, v157
	v_add_u32_e32 v196, 0x4400, v157
	v_add_u32_e32 v197, 0x4800, v157
	v_add_u32_e32 v198, 0x5000, v157
	v_add_u32_e32 v193, 0x5400, v157
	v_add_u32_e32 v194, 0x5800, v157
	v_add_u32_e32 v195, 0x6000, v157
	v_add_u32_e32 v187, 0x6400, v157
	v_add_u32_e32 v188, 0x6800, v157
	v_add_u32_e32 v189, 0x7200, v157
	v_add_u32_e32 v190, 0x7400, v157
	v_add_u32_e32 v191, 0x7600, v157
	v_add_u32_e32 v192, 0x7800, v157
	v_add_u32_e32 v186, 0x8400, v157
	v_add_u32_e32 v185, 0x8800, v157
	v_add_u32_e32 v184, 0x9400, v157
	v_add_u32_e32 v183, 0x9800, v157
	v_add_u32_e32 v181, 0xa400, v157
	v_add_u32_e32 v174, 0xa800, v157
	v_add_u32_e32 v175, 0xb400, v157
	v_add_u32_e32 v176, 0xb600, v157
	v_add_u32_e32 v177, 0xb800, v157
	v_add_u32_e32 v178, 0xba00, v157
	s_waitcnt vmcnt(0)
	s_barrier
	s_and_saveexec_b64 s[20:21], s[6:7]
	s_cbranch_execz .LBB0_1740
	v_and_b32_e32 v254, 63, v180
	v_lshrrev_b32_e32 v253, 4, v254
	v_mul_u32_u24_e32 v253, 0x840, v253
	v_and_b32_e32 v254, 15, v254
	v_lshl_add_u32 v253, v254, 2, v253
	v_and_b32_e32 v254, 64, v180
	v_lshl_add_u32 v253, v254, 2, v253
	ds_write_b32 v253, v0 offset:0
	ds_write_b32 v253, v1 offset:528
	ds_write_b32 v253, v2 offset:1056
	ds_write_b32 v253, v3 offset:1584
	ds_write_b32 v253, v4 offset:64
	ds_write_b32 v253, v5 offset:592
	ds_write_b32 v253, v6 offset:1120
	ds_write_b32 v253, v7 offset:1648
	ds_write_b32 v253, v8 offset:128
	ds_write_b32 v253, v9 offset:656
	ds_write_b32 v253, v10 offset:1184
	ds_write_b32 v253, v11 offset:1712
	ds_write_b32 v253, v12 offset:192
	ds_write_b32 v253, v13 offset:720
	ds_write_b32 v253, v14 offset:1248
	ds_write_b32 v253, v15 offset:1776
	ds_write_b32 v253, v16 offset:8448
	ds_write_b32 v253, v17 offset:8976
	ds_write_b32 v253, v18 offset:9504
	ds_write_b32 v253, v19 offset:10032
	ds_write_b32 v253, v20 offset:8512
	ds_write_b32 v253, v21 offset:9040
	ds_write_b32 v253, v22 offset:9568
	ds_write_b32 v253, v23 offset:10096
	ds_write_b32 v253, v24 offset:8576
	ds_write_b32 v253, v25 offset:9104
	ds_write_b32 v253, v26 offset:9632
	ds_write_b32 v253, v27 offset:10160
	ds_write_b32 v253, v28 offset:8640
	ds_write_b32 v253, v29 offset:9168
	ds_write_b32 v253, v30 offset:9696
	ds_write_b32 v253, v31 offset:10224
	ds_write_b32 v253, v32 offset:16896
	ds_write_b32 v253, v33 offset:17424
	ds_write_b32 v253, v34 offset:17952
	ds_write_b32 v253, v35 offset:18480
	ds_write_b32 v253, v36 offset:16960
	ds_write_b32 v253, v37 offset:17488
	ds_write_b32 v253, v38 offset:18016
	ds_write_b32 v253, v39 offset:18544
	ds_write_b32 v253, v40 offset:17024
	ds_write_b32 v253, v41 offset:17552
	ds_write_b32 v253, v42 offset:18080
	ds_write_b32 v253, v43 offset:18608
	ds_write_b32 v253, v44 offset:17088
	ds_write_b32 v253, v45 offset:17616
	ds_write_b32 v253, v46 offset:18144
	ds_write_b32 v253, v47 offset:18672
	ds_write_b32 v253, v48 offset:25344
	ds_write_b32 v253, v49 offset:25872
	ds_write_b32 v253, v50 offset:26400
	ds_write_b32 v253, v51 offset:26928
	ds_write_b32 v253, v52 offset:25408
	ds_write_b32 v253, v53 offset:25936
	ds_write_b32 v253, v54 offset:26464
	ds_write_b32 v253, v55 offset:26992
	ds_write_b32 v253, v56 offset:25472
	ds_write_b32 v253, v57 offset:26000
	ds_write_b32 v253, v58 offset:26528
	ds_write_b32 v253, v59 offset:27056
	ds_write_b32 v253, v60 offset:25536
	ds_write_b32 v253, v61 offset:26064
	ds_write_b32 v253, v62 offset:26592
	ds_write_b32 v253, v63 offset:27120
	ds_write_b32 v253, v64 offset:33792
	ds_write_b32 v253, v65 offset:34320
	ds_write_b32 v253, v66 offset:34848
	ds_write_b32 v253, v67 offset:35376
	ds_write_b32 v253, v68 offset:33856
	ds_write_b32 v253, v69 offset:34384
	ds_write_b32 v253, v70 offset:34912
	ds_write_b32 v253, v71 offset:35440
	ds_write_b32 v253, v72 offset:33920
	ds_write_b32 v253, v73 offset:34448
	ds_write_b32 v253, v74 offset:34976
	ds_write_b32 v253, v75 offset:35504
	ds_write_b32 v253, v76 offset:33984
	ds_write_b32 v253, v77 offset:34512
	ds_write_b32 v253, v78 offset:35040
	ds_write_b32 v253, v79 offset:35568
	ds_write_b32 v253, v80 offset:42240
	ds_write_b32 v253, v81 offset:42768
	ds_write_b32 v253, v82 offset:43296
	ds_write_b32 v253, v83 offset:43824
	ds_write_b32 v253, v84 offset:42304
	ds_write_b32 v253, v85 offset:42832
	ds_write_b32 v253, v86 offset:43360
	ds_write_b32 v253, v87 offset:43888
	ds_write_b32 v253, v88 offset:42368
	ds_write_b32 v253, v89 offset:42896
	ds_write_b32 v253, v90 offset:43424
	ds_write_b32 v253, v91 offset:43952
	ds_write_b32 v253, v92 offset:42432
	ds_write_b32 v253, v93 offset:42960
	ds_write_b32 v253, v94 offset:43488
	ds_write_b32 v253, v95 offset:44016
	ds_write_b32 v253, v96 offset:50688
	ds_write_b32 v253, v97 offset:51216
	ds_write_b32 v253, v98 offset:51744
	ds_write_b32 v253, v99 offset:52272
	ds_write_b32 v253, v100 offset:50752
	ds_write_b32 v253, v101 offset:51280
	ds_write_b32 v253, v102 offset:51808
	ds_write_b32 v253, v103 offset:52336
	ds_write_b32 v253, v104 offset:50816
	ds_write_b32 v253, v105 offset:51344
	ds_write_b32 v253, v106 offset:51872
	ds_write_b32 v253, v107 offset:52400
	ds_write_b32 v253, v108 offset:50880
	ds_write_b32 v253, v109 offset:51408
	ds_write_b32 v253, v110 offset:51936
	ds_write_b32 v253, v111 offset:52464
	ds_write_b32 v253, v112 offset:59136
	ds_write_b32 v253, v113 offset:59664
	ds_write_b32 v253, v114 offset:60192
	ds_write_b32 v253, v115 offset:60720
	ds_write_b32 v253, v116 offset:59200
	ds_write_b32 v253, v117 offset:59728
	ds_write_b32 v253, v118 offset:60256
	ds_write_b32 v253, v119 offset:60784
	ds_write_b32 v253, v120 offset:59264
	ds_write_b32 v253, v121 offset:59792
	ds_write_b32 v253, v122 offset:60320
	ds_write_b32 v253, v123 offset:60848
	ds_write_b32 v253, v124 offset:59328
	ds_write_b32 v253, v125 offset:59856
	ds_write_b32 v253, v126 offset:60384
	ds_write_b32 v253, v127 offset:60912
